# stack3 + EpiResidNorm fp16 head (F1b-l1, F2b x2): gate pair 2 + first 6 residual loads issued before the gate wait
# speedup vs baseline: 1.0009x; 1.0009x over previous
;     __device__ __forceinline__ void operator()(f32x4 (&acc)[2][2][4][2], const Unit& u, int wr, int wc, int fr_, int fq_) const {
;     ...
;         const bool lat = u.pm < NLAT_TILES; const int rb = lat ? (u.pm >> 3) : 16; const size_t t0 = (size_t)(lat ? u.pm : u.pm - NLAT_TILES) * BM * DM;
;         const int col0 = u.pn * BM + wc * 32 + 8 * fq; const float* gp = mod + (size_t)rb * NMODC + gi * DM + col0;
;         f32x4 gv[2][2];
; #pragma unroll
;         for (int bj = 0; bj < 2; ++bj)
; #pragma unroll
;             for (int n = 0; n < 2; ++n) gv[bj][n] = *(const f32x4*)(gp + bj * HALF + 4 * n) * s;
;     ...
;         } else { const bf16_t* base = (const bf16_t*)(lat ? base_lat : base_ctx) + roff;
; #pragma unroll
;             for (int ai = 0; ai < 2; ++ai) { u32x4 bw[4][2];
; #pragma unroll
;                 for (int m = 0; m < 4; ++m)
; #pragma unroll
;                     for (int bj = 0; bj < 2; ++bj) bw[m][bj] = *(const u32x4*)(base + (size_t)(ai * HALF + m * 16) * DM + bj * HALF);
; #pragma unroll
;                 for (int m = 0; m < 4; ++m)
; #pragma unroll
;                     for (int bj = 0; bj < 2; ++bj) { f32x4 b0, b1; unpack8h(bw[m][bj], b0, b1); acc[ai][bj][m][0] = b0 + gv[bj][0] * acc[ai][bj][m][0]; acc[ai][bj][m][1] = b1 + gv[bj][1] * acc[ai][bj][m][1]; }
.LBB0_310:
	s_add_i32 s29, s28, 0xffffff80
	s_and_b64 s[34:35], s[36:37], exec
	s_cselect_b32 s40, s28, s29
	s_lshl_b32 s29, s30, 8
	s_ashr_i32 s41, s40, 31
	s_or_b32 s29, s29, s84
	v_lshlrev_b32_e32 v200, 3, v168
	s_lshl_b64 s[8:9], s[8:9], 2
	v_add_u32_e32 v146, s29, v200
	s_add_u32 s34, s56, s8
	s_addc_u32 s35, s60, s9
	v_ashrrev_i32_e32 v147, 31, v146
	v_lshl_add_u64 v[130:131], v[146:147], 2, s[34:35]
	s_mov_b64 s[8:9], 0x4000
	v_lshl_add_u64 v[138:139], v[130:131], 0, s[8:9]
	v_add_co_u32_e32 v130, vcc, s87, v130
	v_add_u32_e32 v198, s83, v169
	s_nop 0
	v_addc_co_u32_e32 v131, vcc, 0, v131, vcc
	global_load_dwordx4 v[130:133], v[130:131], off
	s_nop 0
	global_load_dwordx4 v[134:137], v[138:139], off offset:16
	v_ashrrev_i32_e32 v199, 31, v198
	s_lshl_b64 s[8:9], s[40:41], 19
	global_load_dwordx4 v[220:223], v[138:139], off offset:528
	global_load_dwordx4 v[224:227], v[138:139], off offset:512
	v_lshlrev_b64 v[228:229], 11, v[198:199]
	v_lshl_add_u64 v[228:229], v[228:229], 0, s[8:9]
	v_lshl_add_u64 v[148:149], v[228:229], 0, v[146:147]
	v_lshl_add_u64 v[166:167], v[148:149], 1, s[0:1]
	global_load_dwordx4 v[170:173], v[166:167], off
	global_load_dwordx4 v[174:177], v[166:167], off offset:256
	v_add_co_u32_e32 v228, vcc, s75, v166
	s_nop 1
	v_addc_co_u32_e32 v229, vcc, 0, v167, vcc
	global_load_dwordx4 v[208:211], v[228:229], off
	global_load_dwordx4 v[212:215], v[228:229], off offset:256
	v_add_co_u32_e32 v228, vcc, s46, v166
	s_nop 1
	v_addc_co_u32_e32 v229, vcc, 0, v167, vcc
	global_load_dwordx4 v[142:145], v[228:229], off
	global_load_dwordx4 v[138:141], v[228:229], off offset:256
	s_waitcnt vmcnt(6)
	v_pk_mul_f32 v[164:165], v[132:133], 0.5 op_sel_hi:[1,0]
	v_pk_mul_f32 v[162:163], v[130:131], 0.5 op_sel_hi:[1,0]
	v_pk_mul_f32 v[160:161], v[136:137], 0.5 op_sel_hi:[1,0]
	v_pk_mul_f32 v[158:159], v[134:135], 0.5 op_sel_hi:[1,0]
	v_pk_mul_f32 v[150:151], v[220:221], 0.5 op_sel_hi:[1,0]
	v_pk_mul_f32 v[156:157], v[226:227], 0.5 op_sel_hi:[1,0]
	v_pk_mul_f32 v[154:155], v[224:225], 0.5 op_sel_hi:[1,0]
	v_pk_mul_f32 v[152:153], v[222:223], 0.5 op_sel_hi:[1,0]
	v_add_co_u32_e32 v130, vcc, s80, v166
	s_nop 1
	v_addc_co_u32_e32 v131, vcc, 0, v167, vcc
	global_load_dwordx4 v[134:137], v[130:131], off
	s_nop 0
	global_load_dwordx4 v[130:133], v[130:131], off offset:256
	s_mov_b32 s0, 0x90000
	s_waitcnt vmcnt(7)
	v_cvt_f32_f16_e32 v202, v172
	v_cvt_f32_f16_sdwa v203, v172 dst_sel:DWORD dst_unused:UNUSED_PAD src0_sel:WORD_1
	v_cvt_f32_f16_e32 v172, v173
	v_cvt_f32_f16_sdwa v173, v173 dst_sel:DWORD dst_unused:UNUSED_PAD src0_sel:WORD_1
	v_cvt_f32_f16_e32 v216, v170
	v_cvt_f32_f16_sdwa v217, v170 dst_sel:DWORD dst_unused:UNUSED_PAD src0_sel:WORD_1
	v_cvt_f32_f16_e32 v170, v171
	v_cvt_f32_f16_sdwa v171, v171 dst_sel:DWORD dst_unused:UNUSED_PAD src0_sel:WORD_1
	v_pk_fma_f32 v[24:25], v[24:25], v[160:161], v[172:173]
	s_waitcnt vmcnt(6)
	v_cvt_f32_f16_e32 v172, v177
	v_cvt_f32_f16_sdwa v173, v177 dst_sel:DWORD dst_unused:UNUSED_PAD src0_sel:WORD_1
	v_pk_fma_f32 v[32:33], v[32:33], v[164:165], v[170:171]
	v_cvt_f32_f16_e32 v170, v176
	v_cvt_f32_f16_sdwa v171, v176 dst_sel:DWORD dst_unused:UNUSED_PAD src0_sel:WORD_1
	v_pk_fma_f32 v[20:21], v[20:21], v[152:153], v[172:173]
	s_waitcnt vmcnt(5)
	v_cvt_f32_f16_e32 v172, v211
	v_cvt_f32_f16_sdwa v173, v211 dst_sel:DWORD dst_unused:UNUSED_PAD src0_sel:WORD_1
	v_pk_fma_f32 v[18:19], v[18:19], v[150:151], v[170:171]
	v_cvt_f32_f16_e32 v170, v210
	v_cvt_f32_f16_sdwa v171, v210 dst_sel:DWORD dst_unused:UNUSED_PAD src0_sel:WORD_1
	v_pk_fma_f32 v[8:9], v[8:9], v[160:161], v[172:173]
	s_waitcnt vmcnt(4)
	v_cvt_f32_f16_e32 v172, v215
	v_cvt_f32_f16_sdwa v173, v215 dst_sel:DWORD dst_unused:UNUSED_PAD src0_sel:WORD_1
	v_pk_fma_f32 v[6:7], v[6:7], v[158:159], v[170:171]
	v_cvt_f32_f16_e32 v170, v214
	v_cvt_f32_f16_sdwa v171, v214 dst_sel:DWORD dst_unused:UNUSED_PAD src0_sel:WORD_1
	v_pk_fma_f32 v[48:49], v[48:49], v[152:153], v[172:173]
	s_waitcnt vmcnt(3)
	v_cvt_f32_f16_e32 v172, v142
	v_cvt_f32_f16_sdwa v173, v142 dst_sel:DWORD dst_unused:UNUSED_PAD src0_sel:WORD_1
	v_pk_fma_f32 v[46:47], v[46:47], v[150:151], v[170:171]
	v_cvt_f32_f16_e32 v170, v144
	v_cvt_f32_f16_sdwa v171, v144 dst_sel:DWORD dst_unused:UNUSED_PAD src0_sel:WORD_1
	v_cvt_f32_f16_e32 v144, v145
	v_cvt_f32_f16_sdwa v145, v145 dst_sel:DWORD dst_unused:UNUSED_PAD src0_sel:WORD_1
	v_cvt_f32_f16_e32 v142, v143
	v_cvt_f32_f16_sdwa v143, v143 dst_sel:DWORD dst_unused:UNUSED_PAD src0_sel:WORD_1
	v_cvt_f32_f16_e32 v176, v174
	v_cvt_f32_f16_sdwa v177, v174 dst_sel:DWORD dst_unused:UNUSED_PAD src0_sel:WORD_1
	v_cvt_f32_f16_e32 v174, v175
	v_cvt_f32_f16_sdwa v175, v175 dst_sel:DWORD dst_unused:UNUSED_PAD src0_sel:WORD_1
	v_pk_fma_f32 v[52:53], v[52:53], v[164:165], v[142:143]
	v_pk_fma_f32 v[56:57], v[56:57], v[160:161], v[144:145]
	s_waitcnt vmcnt(2)
	v_cvt_f32_f16_e32 v142, v140
	v_cvt_f32_f16_sdwa v143, v140 dst_sel:DWORD dst_unused:UNUSED_PAD src0_sel:WORD_1
	v_cvt_f32_f16_e32 v140, v141
	v_cvt_f32_f16_sdwa v141, v141 dst_sel:DWORD dst_unused:UNUSED_PAD src0_sel:WORD_1
	v_cvt_f32_f16_e32 v144, v138
	v_cvt_f32_f16_sdwa v145, v138 dst_sel:DWORD dst_unused:UNUSED_PAD src0_sel:WORD_1
	v_cvt_f32_f16_e32 v138, v139
	v_cvt_f32_f16_sdwa v139, v139 dst_sel:DWORD dst_unused:UNUSED_PAD src0_sel:WORD_1
	v_pk_fma_f32 v[28:29], v[28:29], v[156:157], v[174:175]
	v_pk_fma_f32 v[26:27], v[26:27], v[154:155], v[176:177]
	v_cvt_f32_f16_e32 v174, v208
	v_cvt_f32_f16_sdwa v175, v208 dst_sel:DWORD dst_unused:UNUSED_PAD src0_sel:WORD_1
	v_cvt_f32_f16_e32 v176, v209
	v_cvt_f32_f16_sdwa v177, v209 dst_sel:DWORD dst_unused:UNUSED_PAD src0_sel:WORD_1
	v_pk_fma_f32 v[68:69], v[68:69], v[156:157], v[138:139]
	v_pk_fma_f32 v[72:73], v[72:73], v[152:153], v[140:141]
	s_waitcnt vmcnt(1)
;     __device__ __forceinline__ void operator()(f32x4 (&acc)[2][2][4][2], const Unit& u, int wr, int wc, int fr_, int fq_) const {
;     ...
;         } else { const bf16_t* base = (const bf16_t*)(lat ? base_lat : base_ctx) + roff;
; #pragma unroll
;             for (int ai = 0; ai < 2; ++ai) { u32x4 bw[4][2];
; #pragma unroll
;                 for (int m = 0; m < 4; ++m)
; #pragma unroll
;                     for (int bj = 0; bj < 2; ++bj) bw[m][bj] = *(const u32x4*)(base + (size_t)(ai * HALF + m * 16) * DM + bj * HALF);
; #pragma unroll
;                 for (int m = 0; m < 4; ++m)
; #pragma unroll
;                     for (int bj = 0; bj < 2; ++bj) { f32x4 b0, b1; unpack8h(bw[m][bj], b0, b1); acc[ai][bj][m][0] = b0 + gv[bj][0] * acc[ai][bj][m][0]; acc[ai][bj][m][1] = b1 + gv[bj][1] * acc[ai][bj][m][1]; }
	v_cvt_f32_f16_e32 v138, v136
	v_cvt_f32_f16_sdwa v139, v136 dst_sel:DWORD dst_unused:UNUSED_PAD src0_sel:WORD_1
	v_cvt_f32_f16_e32 v136, v137
	v_cvt_f32_f16_sdwa v137, v137 dst_sel:DWORD dst_unused:UNUSED_PAD src0_sel:WORD_1
	v_cvt_f32_f16_e32 v140, v134
	v_cvt_f32_f16_sdwa v141, v134 dst_sel:DWORD dst_unused:UNUSED_PAD src0_sel:WORD_1
	v_cvt_f32_f16_e32 v134, v135
	v_cvt_f32_f16_sdwa v135, v135 dst_sel:DWORD dst_unused:UNUSED_PAD src0_sel:WORD_1
	v_pk_fma_f32 v[12:13], v[12:13], v[164:165], v[176:177]
	v_pk_fma_f32 v[10:11], v[10:11], v[162:163], v[174:175]
	v_cvt_f32_f16_e32 v174, v212
	v_cvt_f32_f16_sdwa v175, v212 dst_sel:DWORD dst_unused:UNUSED_PAD src0_sel:WORD_1
	v_cvt_f32_f16_e32 v176, v213
	v_cvt_f32_f16_sdwa v177, v213 dst_sel:DWORD dst_unused:UNUSED_PAD src0_sel:WORD_1
	v_pk_fma_f32 v[76:77], v[76:77], v[164:165], v[134:135]
	v_pk_fma_f32 v[80:81], v[80:81], v[160:161], v[136:137]
	s_waitcnt vmcnt(0)
	v_cvt_f32_f16_e32 v134, v132
	v_cvt_f32_f16_sdwa v135, v132 dst_sel:DWORD dst_unused:UNUSED_PAD src0_sel:WORD_1
	v_cvt_f32_f16_e32 v132, v133
	v_cvt_f32_f16_sdwa v133, v133 dst_sel:DWORD dst_unused:UNUSED_PAD src0_sel:WORD_1
	v_cvt_f32_f16_e32 v136, v130
	v_cvt_f32_f16_sdwa v137, v130 dst_sel:DWORD dst_unused:UNUSED_PAD src0_sel:WORD_1
	v_cvt_f32_f16_e32 v130, v131
	v_cvt_f32_f16_sdwa v131, v131 dst_sel:DWORD dst_unused:UNUSED_PAD src0_sel:WORD_1
	v_pk_fma_f32 v[30:31], v[30:31], v[162:163], v[216:217]
	v_pk_fma_f32 v[22:23], v[22:23], v[158:159], v[202:203]
	v_pk_fma_f32 v[44:45], v[44:45], v[156:157], v[176:177]
	v_pk_fma_f32 v[42:43], v[42:43], v[154:155], v[174:175]
	v_pk_fma_f32 v[50:51], v[50:51], v[162:163], v[172:173]
	v_pk_fma_f32 v[54:55], v[54:55], v[158:159], v[170:171]
	v_pk_fma_f32 v[66:67], v[66:67], v[154:155], v[144:145]
	v_pk_fma_f32 v[70:71], v[70:71], v[150:151], v[142:143]
	v_pk_fma_f32 v[74:75], v[74:75], v[162:163], v[140:141]
	v_pk_fma_f32 v[78:79], v[78:79], v[158:159], v[138:139]
	v_pk_fma_f32 v[84:85], v[84:85], v[156:157], v[130:131]
	v_pk_fma_f32 v[82:83], v[82:83], v[154:155], v[136:137]
	v_pk_fma_f32 v[88:89], v[88:89], v[152:153], v[132:133]
	v_pk_fma_f32 v[86:87], v[86:87], v[150:151], v[134:135]
	v_add_co_u32_e32 v130, vcc, s52, v166
	s_nop 1
	v_addc_co_u32_e32 v131, vcc, 0, v167, vcc
	global_load_dwordx4 v[142:145], v[130:131], off
	global_load_dwordx4 v[170:173], v[130:131], off offset:256
	v_add_co_u32_e32 v130, vcc, s0, v166
	s_mov_b32 s0, 0xa0000
	s_nop 0
	v_addc_co_u32_e32 v131, vcc, 0, v167, vcc
	global_load_dwordx4 v[174:177], v[130:131], off
	global_load_dwordx4 v[208:211], v[130:131], off offset:256
	v_add_co_u32_e32 v130, vcc, s0, v166
	s_mov_b32 s0, 0xb0000
	s_nop 0
	v_addc_co_u32_e32 v131, vcc, 0, v167, vcc
	global_load_dwordx4 v[212:215], v[130:131], off
	global_load_dwordx4 v[138:141], v[130:131], off offset:256
	v_add_co_u32_e32 v130, vcc, s0, v166
	s_waitcnt vmcnt(5)
	v_cvt_f32_f16_e32 v166, v144
	v_addc_co_u32_e32 v131, vcc, 0, v167, vcc
	global_load_dwordx4 v[134:137], v[130:131], off
	s_nop 0
	global_load_dwordx4 v[130:133], v[130:131], off offset:256
	v_cvt_f32_f16_sdwa v167, v144 dst_sel:DWORD dst_unused:UNUSED_PAD src0_sel:WORD_1
	v_cvt_f32_f16_e32 v144, v145
	v_cvt_f32_f16_sdwa v145, v145 dst_sel:DWORD dst_unused:UNUSED_PAD src0_sel:WORD_1
	v_cvt_f32_f16_e32 v202, v142
	v_cvt_f32_f16_sdwa v203, v142 dst_sel:DWORD dst_unused:UNUSED_PAD src0_sel:WORD_1
	v_cvt_f32_f16_e32 v142, v143
	v_cvt_f32_f16_sdwa v143, v143 dst_sel:DWORD dst_unused:UNUSED_PAD src0_sel:WORD_1
	v_pk_fma_f32 v[112:113], v[112:113], v[160:161], v[144:145]
	s_waitcnt vmcnt(6)
	v_cvt_f32_f16_e32 v144, v173
	v_cvt_f32_f16_sdwa v145, v173 dst_sel:DWORD dst_unused:UNUSED_PAD src0_sel:WORD_1
	v_pk_fma_f32 v[108:109], v[108:109], v[164:165], v[142:143]
	v_cvt_f32_f16_e32 v142, v172
	v_cvt_f32_f16_sdwa v143, v172 dst_sel:DWORD dst_unused:UNUSED_PAD src0_sel:WORD_1
	v_pk_fma_f32 v[120:121], v[120:121], v[152:153], v[144:145]
	s_waitcnt vmcnt(5)
	v_cvt_f32_f16_e32 v144, v177
	v_cvt_f32_f16_sdwa v145, v177 dst_sel:DWORD dst_unused:UNUSED_PAD src0_sel:WORD_1
	v_pk_fma_f32 v[118:119], v[118:119], v[150:151], v[142:143]
	v_cvt_f32_f16_e32 v142, v176
	v_cvt_f32_f16_sdwa v143, v176 dst_sel:DWORD dst_unused:UNUSED_PAD src0_sel:WORD_1
	v_pk_fma_f32 v[128:129], v[128:129], v[160:161], v[144:145]
	s_waitcnt vmcnt(4)
	v_cvt_f32_f16_e32 v144, v211
	v_cvt_f32_f16_sdwa v145, v211 dst_sel:DWORD dst_unused:UNUSED_PAD src0_sel:WORD_1
	v_pk_fma_f32 v[126:127], v[126:127], v[158:159], v[142:143]
	v_cvt_f32_f16_e32 v142, v210
	v_cvt_f32_f16_sdwa v143, v210 dst_sel:DWORD dst_unused:UNUSED_PAD src0_sel:WORD_1
	v_pk_fma_f32 v[100:101], v[100:101], v[152:153], v[144:145]
	s_waitcnt vmcnt(3)
	v_cvt_f32_f16_e32 v144, v215
	v_cvt_f32_f16_sdwa v145, v215 dst_sel:DWORD dst_unused:UNUSED_PAD src0_sel:WORD_1
	v_pk_fma_f32 v[98:99], v[98:99], v[150:151], v[142:143]
	v_cvt_f32_f16_e32 v142, v214
	v_cvt_f32_f16_sdwa v143, v214 dst_sel:DWORD dst_unused:UNUSED_PAD src0_sel:WORD_1
	v_pk_fma_f32 v[92:93], v[92:93], v[160:161], v[144:145]
	s_waitcnt vmcnt(2)
; #define PG8_LAS __attribute__((address_space(3)))
;     __device__ __forceinline__ void operator()(f32x4 (&acc)[2][2][4][2], const Unit& u, int wr, int wc, int fr_, int fq_) const {
;     ...
;                 for (int m = 0; m < 4; ++m)
; #pragma unroll
;                     for (int bj = 0; bj < 2; ++bj) { f32x4 b0, b1; unpack8h(bw[m][bj], b0, b1); acc[ai][bj][m][0] = b0 + gv[bj][0] * acc[ai][bj][m][0]; acc[ai][bj][m][1] = b1 + gv[bj][1] * acc[ai][bj][m][1]; }
;                 asm volatile("" : "+v"(acc[ai][0][0][0]), "+v"(acc[ai][0][0][1]), "+v"(acc[ai][1][0][0]), "+v"(acc[ai][1][0][1]), "+v"(acc[ai][0][1][0]), "+v"(acc[ai][0][1][1]), "+v"(acc[ai][1][1][0]), "+v"(acc[ai][1][1][1]),
;                                   "+v"(acc[ai][0][2][0]), "+v"(acc[ai][0][2][1]), "+v"(acc[ai][1][2][0]), "+v"(acc[ai][1][2][1]), "+v"(acc[ai][0][3][0]), "+v"(acc[ai][0][3][1]), "+v"(acc[ai][1][3][0]), "+v"(acc[ai][1][3][1]) :: "memory"); }
;         }
;         PG8_LAS float* P = (PG8_LAS float*)xl; PG8_LAS float* S = P + 1024;
; #pragma unroll
;         for (int ai = 0; ai < 2; ++ai)
; #pragma unroll
;             for (int m = 0; m < 4; ++m) { float q = 0.f;
; #pragma unroll
;                 for (int bj = 0; bj < 2; ++bj)
; #pragma unroll
;                     for (int n = 0; n < 2; ++n) { const f32x4 x = acc[ai][bj][m][n]; q += (x[0] * x[0] + x[1] * x[1]) + (x[2] * x[2] + x[3] * x[3]); }
;                 { auto s_ = __builtin_amdgcn_permlane16_swap(__float_as_uint(q), __float_as_uint(q), false, false); q = __uint_as_float(s_[0]) + __uint_as_float(s_[1]); }
;                 { auto s_ = __builtin_amdgcn_permlane32_swap(__float_as_uint(q), __float_as_uint(q), false, false); q = __uint_as_float(s_[0]) + __uint_as_float(s_[1]); }
;                 if (fq == 0) P[(ai * HALF + wr * 64 + m * 16 + fr) * 4 + wc] = q; }
	v_cvt_f32_f16_e32 v144, v138
	v_cvt_f32_f16_sdwa v145, v138 dst_sel:DWORD dst_unused:UNUSED_PAD src0_sel:WORD_1
	v_cvt_f32_f16_e32 v138, v139
	v_cvt_f32_f16_sdwa v139, v139 dst_sel:DWORD dst_unused:UNUSED_PAD src0_sel:WORD_1
	v_pk_fma_f32 v[90:91], v[90:91], v[158:159], v[142:143]
	v_cvt_f32_f16_e32 v142, v140
	v_cvt_f32_f16_sdwa v143, v140 dst_sel:DWORD dst_unused:UNUSED_PAD src0_sel:WORD_1
	v_cvt_f32_f16_e32 v140, v141
	v_cvt_f32_f16_sdwa v141, v141 dst_sel:DWORD dst_unused:UNUSED_PAD src0_sel:WORD_1
	v_pk_fma_f32 v[64:65], v[64:65], v[156:157], v[138:139]
	v_pk_fma_f32 v[110:111], v[110:111], v[158:159], v[166:167]
	v_cvt_f32_f16_e32 v166, v170
	v_pk_fma_f32 v[60:61], v[60:61], v[152:153], v[140:141]
	v_cvt_f32_f16_sdwa v167, v170 dst_sel:DWORD dst_unused:UNUSED_PAD src0_sel:WORD_1
	v_cvt_f32_f16_e32 v170, v171
	v_cvt_f32_f16_sdwa v171, v171 dst_sel:DWORD dst_unused:UNUSED_PAD src0_sel:WORD_1
	v_pk_fma_f32 v[106:107], v[106:107], v[162:163], v[202:203]
	v_pk_fma_f32 v[114:115], v[114:115], v[154:155], v[166:167]
	v_cvt_f32_f16_e32 v166, v174
	v_pk_fma_f32 v[116:117], v[116:117], v[156:157], v[170:171]
	v_cvt_f32_f16_sdwa v167, v174 dst_sel:DWORD dst_unused:UNUSED_PAD src0_sel:WORD_1
	v_cvt_f32_f16_e32 v170, v175
	v_cvt_f32_f16_sdwa v171, v175 dst_sel:DWORD dst_unused:UNUSED_PAD src0_sel:WORD_1
	v_pk_fma_f32 v[62:63], v[62:63], v[154:155], v[144:145]
	v_pk_fma_f32 v[122:123], v[122:123], v[162:163], v[166:167]
	v_cvt_f32_f16_e32 v166, v208
	v_pk_fma_f32 v[124:125], v[124:125], v[164:165], v[170:171]
	v_cvt_f32_f16_sdwa v167, v208 dst_sel:DWORD dst_unused:UNUSED_PAD src0_sel:WORD_1
	v_cvt_f32_f16_e32 v170, v209
	v_cvt_f32_f16_sdwa v171, v209 dst_sel:DWORD dst_unused:UNUSED_PAD src0_sel:WORD_1
	v_pk_fma_f32 v[58:59], v[58:59], v[150:151], v[142:143]
	v_pk_fma_f32 v[102:103], v[102:103], v[154:155], v[166:167]
	v_cvt_f32_f16_e32 v166, v212
	v_pk_fma_f32 v[104:105], v[104:105], v[156:157], v[170:171]
	v_cvt_f32_f16_sdwa v167, v212 dst_sel:DWORD dst_unused:UNUSED_PAD src0_sel:WORD_1
	v_cvt_f32_f16_e32 v170, v213
	v_cvt_f32_f16_sdwa v171, v213 dst_sel:DWORD dst_unused:UNUSED_PAD src0_sel:WORD_1
	v_cmp_eq_u32_e32 vcc, 0, v168
	v_pk_fma_f32 v[94:95], v[94:95], v[162:163], v[166:167]
	v_pk_fma_f32 v[96:97], v[96:97], v[164:165], v[170:171]
	s_waitcnt vmcnt(1)
	v_cvt_f32_f16_e32 v138, v136
	v_cvt_f32_f16_sdwa v139, v136 dst_sel:DWORD dst_unused:UNUSED_PAD src0_sel:WORD_1
	v_cvt_f32_f16_e32 v136, v137
	v_cvt_f32_f16_sdwa v137, v137 dst_sel:DWORD dst_unused:UNUSED_PAD src0_sel:WORD_1
	v_cvt_f32_f16_e32 v140, v134
	v_cvt_f32_f16_sdwa v141, v134 dst_sel:DWORD dst_unused:UNUSED_PAD src0_sel:WORD_1
	v_cvt_f32_f16_e32 v134, v135
	v_cvt_f32_f16_sdwa v135, v135 dst_sel:DWORD dst_unused:UNUSED_PAD src0_sel:WORD_1
	v_pk_fma_f32 v[36:37], v[36:37], v[160:161], v[136:137]
	s_waitcnt vmcnt(0)
	v_cvt_f32_f16_e32 v136, v130
	v_cvt_f32_f16_sdwa v137, v130 dst_sel:DWORD dst_unused:UNUSED_PAD src0_sel:WORD_1
	v_cvt_f32_f16_e32 v130, v131
	v_cvt_f32_f16_sdwa v131, v131 dst_sel:DWORD dst_unused:UNUSED_PAD src0_sel:WORD_1
	v_pk_fma_f32 v[40:41], v[40:41], v[164:165], v[134:135]
	v_cvt_f32_f16_e32 v134, v132
	v_cvt_f32_f16_sdwa v135, v132 dst_sel:DWORD dst_unused:UNUSED_PAD src0_sel:WORD_1
	v_cvt_f32_f16_e32 v132, v133
	v_cvt_f32_f16_sdwa v133, v133 dst_sel:DWORD dst_unused:UNUSED_PAD src0_sel:WORD_1
	v_pk_fma_f32 v[16:17], v[16:17], v[156:157], v[130:131]
	v_mul_f32_e32 v130, v31, v31
	v_mul_f32_e32 v131, v33, v33
	v_fmac_f32_e32 v130, v30, v30
	v_fmac_f32_e32 v131, v32, v32
	v_pk_fma_f32 v[4:5], v[4:5], v[152:153], v[132:133]
	v_add_f32_e32 v130, v130, v131
	v_mul_f32_e32 v131, v23, v23
	v_mul_f32_e32 v132, v25, v25
	v_fmac_f32_e32 v131, v22, v22
	v_fmac_f32_e32 v132, v24, v24
	v_add_f32_e32 v131, v131, v132
	v_add_f32_e32 v130, v130, v131
	v_mul_f32_e32 v131, v27, v27
	v_mul_f32_e32 v132, v29, v29
	v_fmac_f32_e32 v131, v26, v26
	v_fmac_f32_e32 v132, v28, v28
	v_add_f32_e32 v131, v131, v132
	v_add_f32_e32 v130, v131, v130
	v_mul_f32_e32 v131, v19, v19
	v_mul_f32_e32 v132, v21, v21
	v_fmac_f32_e32 v131, v18, v18
	v_fmac_f32_e32 v132, v20, v20
	v_add_f32_e32 v131, v131, v132
	v_add_f32_e32 v130, v131, v130
	v_mov_b32_e32 v131, v130
	v_pk_fma_f32 v[38:39], v[38:39], v[162:163], v[140:141]
	v_pk_fma_f32 v[34:35], v[34:35], v[158:159], v[138:139]
	v_pk_fma_f32 v[14:15], v[14:15], v[154:155], v[136:137]
	v_pk_fma_f32 v[2:3], v[2:3], v[150:151], v[134:135]
	v_permlane16_swap_b32_e32 v130, v131
	v_add_f32_e32 v131, v130, v131
	v_mov_b32_e32 v132, v131
	s_nop 1
	v_permlane32_swap_b32_e32 v131, v132
	v_lshl_add_u32 v130, v198, 4, s4
	s_and_saveexec_b64 s[0:1], vcc
	v_add_f32_e32 v131, v131, v132
	ds_write_b32 v130, v131
	s_or_b64 exec, exec, s[0:1]
	v_mul_f32_e32 v131, v11, v11
	v_mul_f32_e32 v132, v13, v13
	v_fmac_f32_e32 v131, v10, v10
	v_fmac_f32_e32 v132, v12, v12
	v_add_f32_e32 v131, v131, v132
	v_mul_f32_e32 v132, v7, v7
	v_mul_f32_e32 v133, v9, v9
	v_fmac_f32_e32 v132, v6, v6
	v_fmac_f32_e32 v133, v8, v8
	v_add_f32_e32 v132, v132, v133
	v_add_f32_e32 v131, v131, v132
	v_mul_f32_e32 v132, v43, v43
	v_mul_f32_e32 v133, v45, v45
	v_fmac_f32_e32 v132, v42, v42
	v_fmac_f32_e32 v133, v44, v44
	v_add_f32_e32 v132, v132, v133
	v_add_f32_e32 v131, v132, v131
	v_mul_f32_e32 v132, v47, v47
	v_mul_f32_e32 v133, v49, v49
	v_fmac_f32_e32 v132, v46, v46
	v_fmac_f32_e32 v133, v48, v48
	v_add_f32_e32 v132, v132, v133
	v_add_f32_e32 v131, v132, v131
	v_mov_b32_e32 v132, v131
	s_nop 1
	v_permlane16_swap_b32_e32 v131, v132
	v_add_f32_e32 v131, v131, v132
	v_mov_b32_e32 v132, v131
	s_nop 1
	v_permlane32_swap_b32_e32 v131, v132
	s_and_saveexec_b64 s[0:1], vcc
	v_add_f32_e32 v131, v131, v132
;     __device__ __forceinline__ void operator()(f32x4 (&acc)[2][2][4][2], const Unit& u, int wr, int wc, int fr_, int fq_) const {
;     ...
;         for (int ai = 0; ai < 2; ++ai)
; #pragma unroll
;             for (int m = 0; m < 4; ++m) { float q = 0.f;
; #pragma unroll
;                 for (int bj = 0; bj < 2; ++bj)
; #pragma unroll
;                     for (int n = 0; n < 2; ++n) { const f32x4 x = acc[ai][bj][m][n]; q += (x[0] * x[0] + x[1] * x[1]) + (x[2] * x[2] + x[3] * x[3]); }
;                 { auto s_ = __builtin_amdgcn_permlane16_swap(__float_as_uint(q), __float_as_uint(q), false, false); q = __uint_as_float(s_[0]) + __uint_as_float(s_[1]); }
;                 { auto s_ = __builtin_amdgcn_permlane32_swap(__float_as_uint(q), __float_as_uint(q), false, false); q = __uint_as_float(s_[0]) + __uint_as_float(s_[1]); }
;                 if (fq == 0) P[(ai * HALF + wr * 64 + m * 16 + fr) * 4 + wc] = q; }
;         asm volatile("s_waitcnt lgkmcnt(0)" ::: "memory"); __builtin_amdgcn_s_barrier(); asm volatile("" ::: "memory");
	ds_write_b32 v130, v131 offset:256
	s_or_b64 exec, exec, s[0:1]
	v_mul_f32_e32 v131, v51, v51
	v_mul_f32_e32 v132, v53, v53
	v_fmac_f32_e32 v131, v50, v50
	v_fmac_f32_e32 v132, v52, v52
	v_add_f32_e32 v131, v131, v132
	v_mul_f32_e32 v132, v55, v55
	v_mul_f32_e32 v133, v57, v57
	v_fmac_f32_e32 v132, v54, v54
	v_fmac_f32_e32 v133, v56, v56
	v_add_f32_e32 v132, v132, v133
	v_add_f32_e32 v131, v131, v132
	v_mul_f32_e32 v132, v67, v67
	v_mul_f32_e32 v133, v69, v69
	v_fmac_f32_e32 v132, v66, v66
	v_fmac_f32_e32 v133, v68, v68
	v_add_f32_e32 v132, v132, v133
	v_add_f32_e32 v131, v132, v131
	v_mul_f32_e32 v132, v71, v71
	v_mul_f32_e32 v133, v73, v73
	v_fmac_f32_e32 v132, v70, v70
	v_fmac_f32_e32 v133, v72, v72
	v_add_f32_e32 v132, v132, v133
	v_add_f32_e32 v131, v132, v131
	v_mov_b32_e32 v132, v131
	s_nop 1
	v_permlane16_swap_b32_e32 v131, v132
	v_add_f32_e32 v131, v131, v132
	v_mov_b32_e32 v132, v131
	s_nop 1
	v_permlane32_swap_b32_e32 v131, v132
	s_and_saveexec_b64 s[0:1], vcc
	v_add_f32_e32 v131, v131, v132
	ds_write_b32 v130, v131 offset:512
	s_or_b64 exec, exec, s[0:1]
	v_mul_f32_e32 v131, v75, v75
	v_mul_f32_e32 v132, v77, v77
	v_fmac_f32_e32 v131, v74, v74
	v_fmac_f32_e32 v132, v76, v76
	v_add_f32_e32 v131, v131, v132
	v_mul_f32_e32 v132, v79, v79
	v_mul_f32_e32 v133, v81, v81
	v_fmac_f32_e32 v132, v78, v78
	v_fmac_f32_e32 v133, v80, v80
	v_add_f32_e32 v132, v132, v133
	v_add_f32_e32 v131, v131, v132
	v_mul_f32_e32 v132, v83, v83
	v_mul_f32_e32 v133, v85, v85
	v_fmac_f32_e32 v132, v82, v82
	v_fmac_f32_e32 v133, v84, v84
	v_add_f32_e32 v132, v132, v133
	v_add_f32_e32 v131, v132, v131
	v_mul_f32_e32 v132, v87, v87
	v_mul_f32_e32 v133, v89, v89
	v_fmac_f32_e32 v132, v86, v86
	v_fmac_f32_e32 v133, v88, v88
	v_add_f32_e32 v132, v132, v133
	v_add_f32_e32 v131, v132, v131
	v_mov_b32_e32 v132, v131
	s_nop 1
	v_permlane16_swap_b32_e32 v131, v132
	v_add_f32_e32 v131, v131, v132
	v_mov_b32_e32 v132, v131
	s_nop 1
	v_permlane32_swap_b32_e32 v131, v132
	s_and_saveexec_b64 s[0:1], vcc
	v_add_f32_e32 v131, v131, v132
	ds_write_b32 v130, v131 offset:768
	s_or_b64 exec, exec, s[0:1]
	v_mul_f32_e32 v131, v107, v107
	v_mul_f32_e32 v132, v109, v109
	v_fmac_f32_e32 v131, v106, v106
	v_fmac_f32_e32 v132, v108, v108
	v_add_f32_e32 v131, v131, v132
	v_mul_f32_e32 v132, v111, v111
	v_mul_f32_e32 v133, v113, v113
	v_fmac_f32_e32 v132, v110, v110
	v_fmac_f32_e32 v133, v112, v112
	v_add_f32_e32 v132, v132, v133
	v_add_f32_e32 v131, v131, v132
	v_mul_f32_e32 v132, v115, v115
	v_mul_f32_e32 v133, v117, v117
	v_fmac_f32_e32 v132, v114, v114
	v_fmac_f32_e32 v133, v116, v116
	v_add_f32_e32 v132, v132, v133
	v_add_f32_e32 v131, v132, v131
	v_mul_f32_e32 v132, v119, v119
	v_mul_f32_e32 v133, v121, v121
	v_fmac_f32_e32 v132, v118, v118
	v_fmac_f32_e32 v133, v120, v120
	v_add_f32_e32 v132, v132, v133
	v_add_f32_e32 v131, v132, v131
	v_mov_b32_e32 v132, v131
	s_nop 1
	v_permlane16_swap_b32_e32 v131, v132
	v_add_f32_e32 v131, v131, v132
	v_mov_b32_e32 v132, v131
	s_nop 1
	v_permlane32_swap_b32_e32 v131, v132
	s_and_saveexec_b64 s[0:1], vcc
	v_add_f32_e32 v131, v131, v132
	ds_write_b32 v130, v131 offset:2048
	s_or_b64 exec, exec, s[0:1]
	v_mul_f32_e32 v131, v123, v123
	v_mul_f32_e32 v132, v125, v125
	v_fmac_f32_e32 v131, v122, v122
	v_fmac_f32_e32 v132, v124, v124
	v_add_f32_e32 v131, v131, v132
	v_mul_f32_e32 v132, v127, v127
	v_mul_f32_e32 v133, v129, v129
	v_fmac_f32_e32 v132, v126, v126
	v_fmac_f32_e32 v133, v128, v128
	v_add_f32_e32 v132, v132, v133
	v_add_f32_e32 v131, v131, v132
	v_mul_f32_e32 v132, v103, v103
	v_mul_f32_e32 v133, v105, v105
	v_fmac_f32_e32 v132, v102, v102
	v_fmac_f32_e32 v133, v104, v104
	v_add_f32_e32 v132, v132, v133
	v_add_f32_e32 v131, v132, v131
	v_mul_f32_e32 v132, v99, v99
	v_mul_f32_e32 v133, v101, v101
	v_fmac_f32_e32 v132, v98, v98
	v_fmac_f32_e32 v133, v100, v100
	v_add_f32_e32 v132, v132, v133
	v_add_f32_e32 v131, v132, v131
	v_mov_b32_e32 v132, v131
	s_nop 1
	v_permlane16_swap_b32_e32 v131, v132
	v_add_f32_e32 v131, v131, v132
	v_mov_b32_e32 v132, v131
	s_nop 1
	v_permlane32_swap_b32_e32 v131, v132
	s_and_saveexec_b64 s[0:1], vcc
	v_add_f32_e32 v131, v131, v132
	ds_write_b32 v130, v131 offset:2304
	s_or_b64 exec, exec, s[0:1]
	v_mul_f32_e32 v131, v95, v95
	v_mul_f32_e32 v132, v97, v97
	v_fmac_f32_e32 v131, v94, v94
	v_fmac_f32_e32 v132, v96, v96
	v_add_f32_e32 v131, v131, v132
	v_mul_f32_e32 v132, v91, v91
	v_mul_f32_e32 v133, v93, v93
	v_fmac_f32_e32 v132, v90, v90
	v_fmac_f32_e32 v133, v92, v92
	v_add_f32_e32 v132, v132, v133
	v_add_f32_e32 v131, v131, v132
	v_mul_f32_e32 v132, v63, v63
	v_mul_f32_e32 v133, v65, v65
	v_fmac_f32_e32 v132, v62, v62
	v_fmac_f32_e32 v133, v64, v64
	v_add_f32_e32 v132, v132, v133
	v_add_f32_e32 v131, v132, v131
	v_mul_f32_e32 v132, v59, v59
	v_mul_f32_e32 v133, v61, v61
	v_fmac_f32_e32 v132, v58, v58
	v_fmac_f32_e32 v133, v60, v60
	v_add_f32_e32 v132, v132, v133
	v_add_f32_e32 v131, v132, v131
	v_mov_b32_e32 v132, v131
	s_nop 1
	v_permlane16_swap_b32_e32 v131, v132
	v_add_f32_e32 v131, v131, v132
	v_mov_b32_e32 v132, v131
	s_nop 1
	v_permlane32_swap_b32_e32 v131, v132
	s_and_saveexec_b64 s[0:1], vcc
	v_add_f32_e32 v131, v131, v132
	ds_write_b32 v130, v131 offset:2560
	s_or_b64 exec, exec, s[0:1]
	v_mul_f32_e32 v131, v39, v39
	v_mul_f32_e32 v132, v41, v41
	v_fmac_f32_e32 v131, v38, v38
	v_fmac_f32_e32 v132, v40, v40
	v_add_f32_e32 v131, v131, v132
	v_mul_f32_e32 v132, v35, v35
	v_mul_f32_e32 v133, v37, v37
	v_fmac_f32_e32 v132, v34, v34
	v_fmac_f32_e32 v133, v36, v36
	v_add_f32_e32 v132, v132, v133
	v_add_f32_e32 v131, v131, v132
	v_mul_f32_e32 v132, v15, v15
	v_mul_f32_e32 v133, v17, v17
	v_fmac_f32_e32 v132, v14, v14
	v_fmac_f32_e32 v133, v16, v16
	v_add_f32_e32 v132, v132, v133
	v_add_f32_e32 v131, v132, v131
	v_mul_f32_e32 v132, v3, v3
	v_mul_f32_e32 v133, v5, v5
	v_fmac_f32_e32 v132, v2, v2
	v_fmac_f32_e32 v133, v4, v4
	v_add_f32_e32 v132, v132, v133
	v_add_f32_e32 v131, v132, v131
	v_mov_b32_e32 v132, v131
	s_nop 1
	v_permlane16_swap_b32_e32 v131, v132
	v_add_f32_e32 v131, v131, v132
	v_mov_b32_e32 v132, v131
	s_nop 1
	v_permlane32_swap_b32_e32 v131, v132
	s_and_saveexec_b64 s[0:1], vcc
	v_add_f32_e32 v131, v131, v132
	ds_write_b32 v130, v131 offset:2816
	s_or_b64 exec, exec, s[0:1]
	s_waitcnt lgkmcnt(0)
	s_barrier
;     __device__ __forceinline__ void operator()(f32x4 (&acc)[2][2][4][2], const Unit& u, int wr, int wc, int fr_, int fq_) const {
;     ...
;         const int wid = wr * 4 + wc, lane = fq * 16 + fr, row = wid * 32 + (lane & 31);
;         if (lane < 32) { const float t = (P[row * 4 + 0] + P[row * 4 + 1]) + (P[row * 4 + 2] + P[row * 4 + 3]);
;             __hip_atomic_store(xbuf + ((size_t)u.pm * BM + row) * 8 + u.pn, t, __ATOMIC_RELAXED, __HIP_MEMORY_SCOPE_AGENT); }
	v_lshl_add_u32 v201, v168, 4, v169
	v_and_or_b32 v202, v201, 31, s95
	v_cmp_gt_i32_e64 s[8:9], 32, v201
	v_ashrrev_i32_e32 v203, 31, v202
	s_and_saveexec_b64 s[0:1], s[8:9]
	s_cbranch_execz .LBB0_328
	v_lshl_add_u32 v130, v202, 4, 0
	v_add_u32_e32 v130, 0x20540, v130
	ds_read_b128 v[130:133], v130
	s_ashr_i32 s29, s28, 31
	s_lshl_b64 s[40:41], s[28:29], 13
	s_add_u32 s40, s68, s40
	s_addc_u32 s41, s72, s41
	s_waitcnt lgkmcnt(0)
	v_mov_b32_e32 v134, v131
	v_mov_b32_e32 v135, v132
	v_mov_b32_e32 v131, v133
	v_lshlrev_b64 v[132:133], 5, v[202:203]
	v_pk_add_f32 v[130:131], v[134:135], v[130:131]
	v_lshl_add_u64 v[132:133], s[40:41], 0, v[132:133]
	s_ashr_i32 s31, s30, 31
	v_pk_add_f32 v[130:131], v[130:131], v[130:131] op_sel:[0,1] op_sel_hi:[1,0]
	v_lshl_add_u64 v[132:133], s[30:31], 2, v[132:133]
	global_store_dword v[132:133], v130, off sc1

;     __device__ __forceinline__ void operator()(f32x4 (&acc)[2][2][4][2], const Unit& u, int wr, int wc, int fr_, int fq_) const {
;     ...
;         const bool lat = u.pm < NLAT_TILES; const int rb = lat ? (u.pm >> 3) : 16; const size_t t0 = (size_t)(lat ? u.pm : u.pm - NLAT_TILES) * BM * DM;
;         const int col0 = u.pn * BM + wc * 32 + 8 * fq; const float* gp = mod + (size_t)rb * NMODC + gi * DM + col0;
;         f32x4 gv[2][2];
; #pragma unroll
;         for (int bj = 0; bj < 2; ++bj)
; #pragma unroll
;             for (int n = 0; n < 2; ++n) gv[bj][n] = *(const f32x4*)(gp + bj * HALF + 4 * n) * s;
;     ...
;         } else { const bf16_t* base = (const bf16_t*)(lat ? base_lat : base_ctx) + roff;
; #pragma unroll
;             for (int ai = 0; ai < 2; ++ai) { u32x4 bw[4][2];
; #pragma unroll
;                 for (int m = 0; m < 4; ++m)
; #pragma unroll
;                     for (int bj = 0; bj < 2; ++bj) bw[m][bj] = *(const u32x4*)(base + (size_t)(ai * HALF + m * 16) * DM + bj * HALF);
; #pragma unroll
;                 for (int m = 0; m < 4; ++m)
; #pragma unroll
;                     for (int bj = 0; bj < 2; ++bj) { f32x4 b0, b1; unpack8h(bw[m][bj], b0, b1); acc[ai][bj][m][0] = b0 + gv[bj][0] * acc[ai][bj][m][0]; acc[ai][bj][m][1] = b1 + gv[bj][1] * acc[ai][bj][m][1]; }
.LBB0_1426:
	s_add_u32 s23, s43, s26
	s_addc_u32 s25, s50, s27
	s_add_i32 s26, s22, 0xffffff80
	s_and_b64 s[0:1], s[0:1], exec
	s_cselect_b32 s0, s22, s26
	s_lshl_b32 s1, s24, 8
	s_or_b32 s1, s1, s44
	s_lshl_b64 s[8:9], s[8:9], 2
	v_lshl_add_u32 v158, v183, 3, s1
	s_add_u32 s8, s43, s8
	s_addc_u32 s9, s50, s9
	v_ashrrev_i32_e32 v159, 31, v158
	v_lshl_add_u64 v[130:131], v[158:159], 2, s[8:9]
	s_mov_b64 s[8:9], 0x242000
	s_mov_b32 s1, 0x242000
	v_lshl_add_u64 v[138:139], v[130:131], 0, s[8:9]
	v_add_co_u32_e32 v130, vcc, s1, v130
	s_ashr_i32 s1, s0, 31
	s_nop 0
	v_addc_co_u32_e32 v131, vcc, 0, v131, vcc
	global_load_dwordx4 v[130:133], v[130:131], off
	s_nop 0
	global_load_dwordx4 v[134:137], v[138:139], off offset:16
	v_add_u32_e32 v156, s41, v182
	s_lshl_b64 s[0:1], s[0:1], 20
	v_ashrrev_i32_e32 v157, 31, v156
	s_add_u32 s0, s23, s0
	s_addc_u32 s1, s25, s1
	global_load_dwordx4 v[220:223], v[138:139], off offset:528
	global_load_dwordx4 v[224:227], v[138:139], off offset:512
	v_lshlrev_b64 v[228:229], 12, v[156:157]
	v_lshl_add_u64 v[228:229], s[0:1], 0, v[228:229]
	v_lshl_add_u64 v[176:177], v[158:159], 1, v[228:229]
	global_load_dwordx4 v[196:199], v[176:177], off
	global_load_dwordx4 v[200:203], v[176:177], off offset:256
	v_add_co_u32_e32 v228, vcc, s82, v176
	s_nop 1
	v_addc_co_u32_e32 v229, vcc, 0, v177, vcc
	global_load_dwordx4 v[204:207], v[228:229], off
	global_load_dwordx4 v[208:211], v[228:229], off offset:256
	v_add_co_u32_e32 v228, vcc, s95, v176
	s_nop 1
	v_addc_co_u32_e32 v229, vcc, 0, v177, vcc
	global_load_dwordx4 v[142:145], v[228:229], off
	global_load_dwordx4 v[138:141], v[228:229], off offset:256
	s_waitcnt vmcnt(6)
	v_pk_mul_f32 v[174:175], v[132:133], 0.5 op_sel_hi:[1,0]
	v_pk_mul_f32 v[172:173], v[130:131], 0.5 op_sel_hi:[1,0]
	v_pk_mul_f32 v[170:171], v[136:137], 0.5 op_sel_hi:[1,0]
	v_pk_mul_f32 v[168:169], v[134:135], 0.5 op_sel_hi:[1,0]
	v_pk_mul_f32 v[160:161], v[220:221], 0.5 op_sel_hi:[1,0]
	v_pk_mul_f32 v[166:167], v[226:227], 0.5 op_sel_hi:[1,0]
	v_pk_mul_f32 v[164:165], v[224:225], 0.5 op_sel_hi:[1,0]
	v_pk_mul_f32 v[162:163], v[222:223], 0.5 op_sel_hi:[1,0]
	v_add_co_u32_e32 v130, vcc, s91, v176
	s_nop 1
	v_addc_co_u32_e32 v131, vcc, 0, v177, vcc
	global_load_dwordx4 v[134:137], v[130:131], off
	s_nop 0
	global_load_dwordx4 v[130:133], v[130:131], off offset:256
	s_mov_b32 s0, 0x90000
	s_waitcnt vmcnt(7)
	v_cvt_f32_f16_e32 v184, v198
	v_cvt_f32_f16_sdwa v185, v198 dst_sel:DWORD dst_unused:UNUSED_PAD src0_sel:WORD_1
	v_cvt_f32_f16_e32 v188, v199
	v_cvt_f32_f16_sdwa v189, v199 dst_sel:DWORD dst_unused:UNUSED_PAD src0_sel:WORD_1
	v_cvt_f32_f16_e32 v190, v196
	v_pk_fma_f32 v[50:51], v[50:51], v[168:169], v[184:185]
	s_waitcnt vmcnt(6)
	v_cvt_f32_f16_e32 v184, v202
	v_pk_fma_f32 v[52:53], v[52:53], v[170:171], v[188:189]
	v_cvt_f32_f16_sdwa v185, v202 dst_sel:DWORD dst_unused:UNUSED_PAD src0_sel:WORD_1
	v_cvt_f32_f16_e32 v188, v203
	v_cvt_f32_f16_sdwa v189, v203 dst_sel:DWORD dst_unused:UNUSED_PAD src0_sel:WORD_1
	v_cvt_f32_f16_sdwa v191, v196 dst_sel:DWORD dst_unused:UNUSED_PAD src0_sel:WORD_1
	v_pk_fma_f32 v[54:55], v[54:55], v[160:161], v[184:185]
	s_waitcnt vmcnt(5)
	v_cvt_f32_f16_e32 v184, v206
	v_pk_fma_f32 v[56:57], v[56:57], v[162:163], v[188:189]
	v_cvt_f32_f16_sdwa v185, v206 dst_sel:DWORD dst_unused:UNUSED_PAD src0_sel:WORD_1
	v_cvt_f32_f16_e32 v188, v207
	v_cvt_f32_f16_sdwa v189, v207 dst_sel:DWORD dst_unused:UNUSED_PAD src0_sel:WORD_1
	v_cvt_f32_f16_e32 v192, v197
	v_pk_fma_f32 v[70:71], v[70:71], v[168:169], v[184:185]
	s_waitcnt vmcnt(4)
	v_cvt_f32_f16_e32 v184, v210
	v_pk_fma_f32 v[72:73], v[72:73], v[170:171], v[188:189]
	v_cvt_f32_f16_sdwa v185, v210 dst_sel:DWORD dst_unused:UNUSED_PAD src0_sel:WORD_1
	v_cvt_f32_f16_e32 v188, v211
	v_cvt_f32_f16_sdwa v189, v211 dst_sel:DWORD dst_unused:UNUSED_PAD src0_sel:WORD_1
	v_cvt_f32_f16_sdwa v193, v197 dst_sel:DWORD dst_unused:UNUSED_PAD src0_sel:WORD_1
	v_pk_fma_f32 v[94:95], v[94:95], v[160:161], v[184:185]
	s_waitcnt vmcnt(3)
	v_cvt_f32_f16_e32 v184, v144
	v_pk_fma_f32 v[96:97], v[96:97], v[162:163], v[188:189]
	v_cvt_f32_f16_sdwa v185, v144 dst_sel:DWORD dst_unused:UNUSED_PAD src0_sel:WORD_1
	v_cvt_f32_f16_e32 v144, v145
	v_cvt_f32_f16_sdwa v145, v145 dst_sel:DWORD dst_unused:UNUSED_PAD src0_sel:WORD_1
	v_cvt_f32_f16_e32 v188, v142
	v_cvt_f32_f16_sdwa v189, v142 dst_sel:DWORD dst_unused:UNUSED_PAD src0_sel:WORD_1
	v_cvt_f32_f16_e32 v142, v143
	v_cvt_f32_f16_sdwa v143, v143 dst_sel:DWORD dst_unused:UNUSED_PAD src0_sel:WORD_1
	v_pk_fma_f32 v[60:61], v[60:61], v[174:175], v[192:193]
	v_pk_fma_f32 v[58:59], v[58:59], v[172:173], v[190:191]
	v_cvt_f32_f16_e32 v190, v200
	v_cvt_f32_f16_sdwa v191, v200 dst_sel:DWORD dst_unused:UNUSED_PAD src0_sel:WORD_1
	v_cvt_f32_f16_e32 v192, v201
	v_cvt_f32_f16_sdwa v193, v201 dst_sel:DWORD dst_unused:UNUSED_PAD src0_sel:WORD_1
	v_pk_fma_f32 v[100:101], v[100:101], v[174:175], v[142:143]
	v_pk_fma_f32 v[104:105], v[104:105], v[170:171], v[144:145]
	s_waitcnt vmcnt(2)
	v_cvt_f32_f16_e32 v142, v140
	v_cvt_f32_f16_sdwa v143, v140 dst_sel:DWORD dst_unused:UNUSED_PAD src0_sel:WORD_1
	v_cvt_f32_f16_e32 v140, v141
	v_cvt_f32_f16_sdwa v141, v141 dst_sel:DWORD dst_unused:UNUSED_PAD src0_sel:WORD_1
	v_cvt_f32_f16_e32 v144, v138
	v_cvt_f32_f16_sdwa v145, v138 dst_sel:DWORD dst_unused:UNUSED_PAD src0_sel:WORD_1
	v_cvt_f32_f16_e32 v138, v139
	v_cvt_f32_f16_sdwa v139, v139 dst_sel:DWORD dst_unused:UNUSED_PAD src0_sel:WORD_1
	v_pk_fma_f32 v[68:69], v[68:69], v[166:167], v[192:193]
	v_pk_fma_f32 v[66:67], v[66:67], v[164:165], v[190:191]
	v_cvt_f32_f16_e32 v190, v204
	v_cvt_f32_f16_sdwa v191, v204 dst_sel:DWORD dst_unused:UNUSED_PAD src0_sel:WORD_1
	v_cvt_f32_f16_e32 v192, v205
	v_cvt_f32_f16_sdwa v193, v205 dst_sel:DWORD dst_unused:UNUSED_PAD src0_sel:WORD_1
	v_pk_fma_f32 v[108:109], v[108:109], v[166:167], v[138:139]
	v_pk_fma_f32 v[112:113], v[112:113], v[162:163], v[140:141]
	s_waitcnt vmcnt(1)
;     __device__ __forceinline__ void operator()(f32x4 (&acc)[2][2][4][2], const Unit& u, int wr, int wc, int fr_, int fq_) const {
;     ...
;         } else { const bf16_t* base = (const bf16_t*)(lat ? base_lat : base_ctx) + roff;
; #pragma unroll
;             for (int ai = 0; ai < 2; ++ai) { u32x4 bw[4][2];
; #pragma unroll
;                 for (int m = 0; m < 4; ++m)
; #pragma unroll
;                     for (int bj = 0; bj < 2; ++bj) bw[m][bj] = *(const u32x4*)(base + (size_t)(ai * HALF + m * 16) * DM + bj * HALF);
; #pragma unroll
;                 for (int m = 0; m < 4; ++m)
; #pragma unroll
;                     for (int bj = 0; bj < 2; ++bj) { f32x4 b0, b1; unpack8h(bw[m][bj], b0, b1); acc[ai][bj][m][0] = b0 + gv[bj][0] * acc[ai][bj][m][0]; acc[ai][bj][m][1] = b1 + gv[bj][1] * acc[ai][bj][m][1]; }
	v_cvt_f32_f16_e32 v138, v136
	v_cvt_f32_f16_sdwa v139, v136 dst_sel:DWORD dst_unused:UNUSED_PAD src0_sel:WORD_1
	v_cvt_f32_f16_e32 v136, v137
	v_cvt_f32_f16_sdwa v137, v137 dst_sel:DWORD dst_unused:UNUSED_PAD src0_sel:WORD_1
	v_cvt_f32_f16_e32 v140, v134
	v_cvt_f32_f16_sdwa v141, v134 dst_sel:DWORD dst_unused:UNUSED_PAD src0_sel:WORD_1
	v_cvt_f32_f16_e32 v134, v135
	v_cvt_f32_f16_sdwa v135, v135 dst_sel:DWORD dst_unused:UNUSED_PAD src0_sel:WORD_1
	v_pk_fma_f32 v[80:81], v[80:81], v[174:175], v[192:193]
	v_pk_fma_f32 v[78:79], v[78:79], v[172:173], v[190:191]
	v_cvt_f32_f16_e32 v190, v208
	v_cvt_f32_f16_sdwa v191, v208 dst_sel:DWORD dst_unused:UNUSED_PAD src0_sel:WORD_1
	v_cvt_f32_f16_e32 v192, v209
	v_cvt_f32_f16_sdwa v193, v209 dst_sel:DWORD dst_unused:UNUSED_PAD src0_sel:WORD_1
	v_pk_fma_f32 v[116:117], v[116:117], v[174:175], v[134:135]
	v_pk_fma_f32 v[120:121], v[120:121], v[170:171], v[136:137]
	s_waitcnt vmcnt(0)
	v_cvt_f32_f16_e32 v134, v132
	v_cvt_f32_f16_sdwa v135, v132 dst_sel:DWORD dst_unused:UNUSED_PAD src0_sel:WORD_1
	v_cvt_f32_f16_e32 v132, v133
	v_cvt_f32_f16_sdwa v133, v133 dst_sel:DWORD dst_unused:UNUSED_PAD src0_sel:WORD_1
	v_cvt_f32_f16_e32 v136, v130
	v_cvt_f32_f16_sdwa v137, v130 dst_sel:DWORD dst_unused:UNUSED_PAD src0_sel:WORD_1
	v_cvt_f32_f16_e32 v130, v131
	v_cvt_f32_f16_sdwa v131, v131 dst_sel:DWORD dst_unused:UNUSED_PAD src0_sel:WORD_1
	v_pk_fma_f32 v[88:89], v[88:89], v[166:167], v[192:193]
	v_pk_fma_f32 v[86:87], v[86:87], v[164:165], v[190:191]
	v_pk_fma_f32 v[98:99], v[98:99], v[172:173], v[188:189]
	v_pk_fma_f32 v[102:103], v[102:103], v[168:169], v[184:185]
	v_pk_fma_f32 v[106:107], v[106:107], v[164:165], v[144:145]
	v_pk_fma_f32 v[110:111], v[110:111], v[160:161], v[142:143]
	v_pk_fma_f32 v[114:115], v[114:115], v[172:173], v[140:141]
	v_pk_fma_f32 v[118:119], v[118:119], v[168:169], v[138:139]
	v_pk_fma_f32 v[124:125], v[124:125], v[166:167], v[130:131]
	v_pk_fma_f32 v[122:123], v[122:123], v[164:165], v[136:137]
	v_pk_fma_f32 v[128:129], v[128:129], v[162:163], v[132:133]
	v_pk_fma_f32 v[126:127], v[126:127], v[160:161], v[134:135]
	v_add_co_u32_e32 v130, vcc, s52, v176
	s_nop 1
	v_addc_co_u32_e32 v131, vcc, 0, v177, vcc
	global_load_dwordx4 v[142:145], v[130:131], off
	global_load_dwordx4 v[196:199], v[130:131], off offset:256
	v_add_co_u32_e32 v130, vcc, s0, v176
	s_mov_b32 s0, 0xa0000
	s_nop 0
	v_addc_co_u32_e32 v131, vcc, 0, v177, vcc
	global_load_dwordx4 v[200:203], v[130:131], off
	global_load_dwordx4 v[204:207], v[130:131], off offset:256
	v_add_co_u32_e32 v130, vcc, s0, v176
	s_mov_b32 s0, 0xb0000
	s_nop 0
	v_addc_co_u32_e32 v131, vcc, 0, v177, vcc
	global_load_dwordx4 v[208:211], v[130:131], off
	global_load_dwordx4 v[138:141], v[130:131], off offset:256
	v_add_co_u32_e32 v130, vcc, s0, v176
	s_waitcnt vmcnt(5)
	v_cvt_f32_f16_e32 v176, v144
	v_addc_co_u32_e32 v131, vcc, 0, v177, vcc
	global_load_dwordx4 v[134:137], v[130:131], off
	s_nop 0
	global_load_dwordx4 v[130:133], v[130:131], off offset:256
	v_cvt_f32_f16_sdwa v177, v144 dst_sel:DWORD dst_unused:UNUSED_PAD src0_sel:WORD_1
	v_cvt_f32_f16_e32 v144, v145
	v_cvt_f32_f16_sdwa v145, v145 dst_sel:DWORD dst_unused:UNUSED_PAD src0_sel:WORD_1
	v_cvt_f32_f16_e32 v184, v142
	v_cvt_f32_f16_sdwa v185, v142 dst_sel:DWORD dst_unused:UNUSED_PAD src0_sel:WORD_1
	v_cvt_f32_f16_e32 v142, v143
	v_cvt_f32_f16_sdwa v143, v143 dst_sel:DWORD dst_unused:UNUSED_PAD src0_sel:WORD_1
	v_pk_fma_f32 v[84:85], v[84:85], v[170:171], v[144:145]
	s_waitcnt vmcnt(6)
	v_cvt_f32_f16_e32 v144, v199
	v_cvt_f32_f16_sdwa v145, v199 dst_sel:DWORD dst_unused:UNUSED_PAD src0_sel:WORD_1
	v_pk_fma_f32 v[92:93], v[92:93], v[174:175], v[142:143]
	v_cvt_f32_f16_e32 v142, v198
	v_cvt_f32_f16_sdwa v143, v198 dst_sel:DWORD dst_unused:UNUSED_PAD src0_sel:WORD_1
	v_pk_fma_f32 v[64:65], v[64:65], v[162:163], v[144:145]
	s_waitcnt vmcnt(5)
	v_cvt_f32_f16_e32 v144, v203
	v_cvt_f32_f16_sdwa v145, v203 dst_sel:DWORD dst_unused:UNUSED_PAD src0_sel:WORD_1
	v_pk_fma_f32 v[62:63], v[62:63], v[160:161], v[142:143]
	v_cvt_f32_f16_e32 v142, v202
	v_cvt_f32_f16_sdwa v143, v202 dst_sel:DWORD dst_unused:UNUSED_PAD src0_sel:WORD_1
	v_pk_fma_f32 v[44:45], v[44:45], v[170:171], v[144:145]
	s_waitcnt vmcnt(4)
	v_cvt_f32_f16_e32 v144, v207
	v_cvt_f32_f16_sdwa v145, v207 dst_sel:DWORD dst_unused:UNUSED_PAD src0_sel:WORD_1
	v_pk_fma_f32 v[42:43], v[42:43], v[168:169], v[142:143]
	v_cvt_f32_f16_e32 v142, v206
	v_cvt_f32_f16_sdwa v143, v206 dst_sel:DWORD dst_unused:UNUSED_PAD src0_sel:WORD_1
	v_pk_fma_f32 v[36:37], v[36:37], v[162:163], v[144:145]
	s_waitcnt vmcnt(3)
	v_cvt_f32_f16_e32 v144, v211
	v_cvt_f32_f16_sdwa v145, v211 dst_sel:DWORD dst_unused:UNUSED_PAD src0_sel:WORD_1
	v_pk_fma_f32 v[34:35], v[34:35], v[160:161], v[142:143]
	v_cvt_f32_f16_e32 v142, v210
	v_cvt_f32_f16_sdwa v143, v210 dst_sel:DWORD dst_unused:UNUSED_PAD src0_sel:WORD_1
	v_pk_fma_f32 v[28:29], v[28:29], v[170:171], v[144:145]
	s_waitcnt vmcnt(2)
; #define PG8_LAS __attribute__((address_space(3)))
;     __device__ __forceinline__ void operator()(f32x4 (&acc)[2][2][4][2], const Unit& u, int wr, int wc, int fr_, int fq_) const {
;     ...
;                 for (int m = 0; m < 4; ++m)
; #pragma unroll
;                     for (int bj = 0; bj < 2; ++bj) { f32x4 b0, b1; unpack8h(bw[m][bj], b0, b1); acc[ai][bj][m][0] = b0 + gv[bj][0] * acc[ai][bj][m][0]; acc[ai][bj][m][1] = b1 + gv[bj][1] * acc[ai][bj][m][1]; }
;                 asm volatile("" : "+v"(acc[ai][0][0][0]), "+v"(acc[ai][0][0][1]), "+v"(acc[ai][1][0][0]), "+v"(acc[ai][1][0][1]), "+v"(acc[ai][0][1][0]), "+v"(acc[ai][0][1][1]), "+v"(acc[ai][1][1][0]), "+v"(acc[ai][1][1][1]),
;                                   "+v"(acc[ai][0][2][0]), "+v"(acc[ai][0][2][1]), "+v"(acc[ai][1][2][0]), "+v"(acc[ai][1][2][1]), "+v"(acc[ai][0][3][0]), "+v"(acc[ai][0][3][1]), "+v"(acc[ai][1][3][0]), "+v"(acc[ai][1][3][1]) :: "memory"); }
;         }
;         PG8_LAS float* P = (PG8_LAS float*)xl; PG8_LAS float* S = P + 1024;
; #pragma unroll
;         for (int ai = 0; ai < 2; ++ai)
; #pragma unroll
;             for (int m = 0; m < 4; ++m) { float q = 0.f;
; #pragma unroll
;                 for (int bj = 0; bj < 2; ++bj)
; #pragma unroll
;                     for (int n = 0; n < 2; ++n) { const f32x4 x = acc[ai][bj][m][n]; q += (x[0] * x[0] + x[1] * x[1]) + (x[2] * x[2] + x[3] * x[3]); }
;                 { auto s_ = __builtin_amdgcn_permlane16_swap(__float_as_uint(q), __float_as_uint(q), false, false); q = __uint_as_float(s_[0]) + __uint_as_float(s_[1]); }
;                 { auto s_ = __builtin_amdgcn_permlane32_swap(__float_as_uint(q), __float_as_uint(q), false, false); q = __uint_as_float(s_[0]) + __uint_as_float(s_[1]); }
;                 if (fq == 0) P[(ai * HALF + wr * 64 + m * 16 + fr) * 4 + wc] = q; }
	v_cvt_f32_f16_e32 v144, v138
	v_cvt_f32_f16_sdwa v145, v138 dst_sel:DWORD dst_unused:UNUSED_PAD src0_sel:WORD_1
	v_cvt_f32_f16_e32 v138, v139
	v_cvt_f32_f16_sdwa v139, v139 dst_sel:DWORD dst_unused:UNUSED_PAD src0_sel:WORD_1
	v_pk_fma_f32 v[26:27], v[26:27], v[168:169], v[142:143]
	v_cvt_f32_f16_e32 v142, v140
	v_cvt_f32_f16_sdwa v143, v140 dst_sel:DWORD dst_unused:UNUSED_PAD src0_sel:WORD_1
	v_cvt_f32_f16_e32 v140, v141
	v_cvt_f32_f16_sdwa v141, v141 dst_sel:DWORD dst_unused:UNUSED_PAD src0_sel:WORD_1
	v_pk_fma_f32 v[24:25], v[24:25], v[166:167], v[138:139]
	v_pk_fma_f32 v[90:91], v[90:91], v[172:173], v[184:185]
	v_pk_fma_f32 v[82:83], v[82:83], v[168:169], v[176:177]
	v_pk_fma_f32 v[20:21], v[20:21], v[162:163], v[140:141]
	v_cvt_f32_f16_e32 v176, v196
	v_cvt_f32_f16_sdwa v177, v196 dst_sel:DWORD dst_unused:UNUSED_PAD src0_sel:WORD_1
	v_cvt_f32_f16_e32 v184, v197
	v_cvt_f32_f16_sdwa v185, v197 dst_sel:DWORD dst_unused:UNUSED_PAD src0_sel:WORD_1
	v_pk_fma_f32 v[22:23], v[22:23], v[164:165], v[144:145]
	v_pk_fma_f32 v[74:75], v[74:75], v[164:165], v[176:177]
	v_cvt_f32_f16_e32 v176, v200
	v_pk_fma_f32 v[76:77], v[76:77], v[166:167], v[184:185]
	v_cvt_f32_f16_sdwa v177, v200 dst_sel:DWORD dst_unused:UNUSED_PAD src0_sel:WORD_1
	v_cvt_f32_f16_e32 v184, v201
	v_cvt_f32_f16_sdwa v185, v201 dst_sel:DWORD dst_unused:UNUSED_PAD src0_sel:WORD_1
	v_pk_fma_f32 v[18:19], v[18:19], v[160:161], v[142:143]
	v_pk_fma_f32 v[46:47], v[46:47], v[172:173], v[176:177]
	v_cvt_f32_f16_e32 v176, v204
	v_pk_fma_f32 v[48:49], v[48:49], v[174:175], v[184:185]
	v_cvt_f32_f16_sdwa v177, v204 dst_sel:DWORD dst_unused:UNUSED_PAD src0_sel:WORD_1
	v_cvt_f32_f16_e32 v184, v205
	v_cvt_f32_f16_sdwa v185, v205 dst_sel:DWORD dst_unused:UNUSED_PAD src0_sel:WORD_1
	v_cmp_eq_u32_e32 vcc, 0, v183
	v_pk_fma_f32 v[38:39], v[38:39], v[164:165], v[176:177]
	v_cvt_f32_f16_e32 v176, v208
	v_pk_fma_f32 v[40:41], v[40:41], v[166:167], v[184:185]
	v_cvt_f32_f16_sdwa v177, v208 dst_sel:DWORD dst_unused:UNUSED_PAD src0_sel:WORD_1
	v_cvt_f32_f16_e32 v184, v209
	v_cvt_f32_f16_sdwa v185, v209 dst_sel:DWORD dst_unused:UNUSED_PAD src0_sel:WORD_1
	v_pk_fma_f32 v[30:31], v[30:31], v[172:173], v[176:177]
	v_pk_fma_f32 v[32:33], v[32:33], v[174:175], v[184:185]
	s_waitcnt vmcnt(1)
	v_cvt_f32_f16_e32 v138, v136
	v_cvt_f32_f16_sdwa v139, v136 dst_sel:DWORD dst_unused:UNUSED_PAD src0_sel:WORD_1
	v_cvt_f32_f16_e32 v136, v137
	v_cvt_f32_f16_sdwa v137, v137 dst_sel:DWORD dst_unused:UNUSED_PAD src0_sel:WORD_1
	v_cvt_f32_f16_e32 v140, v134
	v_cvt_f32_f16_sdwa v141, v134 dst_sel:DWORD dst_unused:UNUSED_PAD src0_sel:WORD_1
	v_cvt_f32_f16_e32 v134, v135
	v_cvt_f32_f16_sdwa v135, v135 dst_sel:DWORD dst_unused:UNUSED_PAD src0_sel:WORD_1
	v_pk_fma_f32 v[12:13], v[12:13], v[170:171], v[136:137]
	s_waitcnt vmcnt(0)
	v_cvt_f32_f16_e32 v136, v130
	v_cvt_f32_f16_sdwa v137, v130 dst_sel:DWORD dst_unused:UNUSED_PAD src0_sel:WORD_1
	v_cvt_f32_f16_e32 v130, v131
	v_cvt_f32_f16_sdwa v131, v131 dst_sel:DWORD dst_unused:UNUSED_PAD src0_sel:WORD_1
	v_pk_fma_f32 v[16:17], v[16:17], v[174:175], v[134:135]
	v_cvt_f32_f16_e32 v134, v132
	v_cvt_f32_f16_sdwa v135, v132 dst_sel:DWORD dst_unused:UNUSED_PAD src0_sel:WORD_1
	v_cvt_f32_f16_e32 v132, v133
	v_cvt_f32_f16_sdwa v133, v133 dst_sel:DWORD dst_unused:UNUSED_PAD src0_sel:WORD_1
	v_pk_fma_f32 v[8:9], v[8:9], v[166:167], v[130:131]
	v_mul_f32_e32 v130, v59, v59
	v_mul_f32_e32 v131, v61, v61
	v_fmac_f32_e32 v130, v58, v58
	v_fmac_f32_e32 v131, v60, v60
	v_pk_fma_f32 v[4:5], v[4:5], v[162:163], v[132:133]
	v_add_f32_e32 v130, v130, v131
	v_mul_f32_e32 v131, v51, v51
	v_mul_f32_e32 v132, v53, v53
	v_fmac_f32_e32 v131, v50, v50
	v_fmac_f32_e32 v132, v52, v52
	v_add_f32_e32 v131, v131, v132
	v_add_f32_e32 v130, v130, v131
	v_mul_f32_e32 v131, v67, v67
	v_mul_f32_e32 v132, v69, v69
	v_fmac_f32_e32 v131, v66, v66
	v_fmac_f32_e32 v132, v68, v68
	v_add_f32_e32 v131, v131, v132
	v_add_f32_e32 v130, v131, v130
	v_mul_f32_e32 v131, v55, v55
	v_mul_f32_e32 v132, v57, v57
	v_fmac_f32_e32 v131, v54, v54
	v_fmac_f32_e32 v132, v56, v56
	v_add_f32_e32 v131, v131, v132
	v_add_f32_e32 v130, v131, v130
	v_mov_b32_e32 v131, v130
	v_pk_fma_f32 v[14:15], v[14:15], v[172:173], v[140:141]
	v_pk_fma_f32 v[10:11], v[10:11], v[168:169], v[138:139]
	v_pk_fma_f32 v[6:7], v[6:7], v[164:165], v[136:137]
	v_pk_fma_f32 v[2:3], v[2:3], v[160:161], v[134:135]
	v_permlane16_swap_b32_e32 v130, v131
	v_add_f32_e32 v131, v130, v131
	v_mov_b32_e32 v132, v131
	s_nop 1
	v_permlane32_swap_b32_e32 v131, v132
	v_lshl_add_u32 v130, v156, 4, s61
	s_and_saveexec_b64 s[0:1], vcc
	v_add_f32_e32 v131, v131, v132
	ds_write_b32 v130, v131
	s_or_b64 exec, exec, s[0:1]
	v_mul_f32_e32 v131, v79, v79
	v_mul_f32_e32 v132, v81, v81
	v_fmac_f32_e32 v131, v78, v78
	v_fmac_f32_e32 v132, v80, v80
	v_add_f32_e32 v131, v131, v132
	v_mul_f32_e32 v132, v71, v71
	v_mul_f32_e32 v133, v73, v73
	v_fmac_f32_e32 v132, v70, v70
	v_fmac_f32_e32 v133, v72, v72
	v_add_f32_e32 v132, v132, v133
	v_add_f32_e32 v131, v131, v132
	v_mul_f32_e32 v132, v87, v87
	v_mul_f32_e32 v133, v89, v89
	v_fmac_f32_e32 v132, v86, v86
	v_fmac_f32_e32 v133, v88, v88
	v_add_f32_e32 v132, v132, v133
	v_add_f32_e32 v131, v132, v131
	v_mul_f32_e32 v132, v95, v95
	v_mul_f32_e32 v133, v97, v97
	v_fmac_f32_e32 v132, v94, v94
	v_fmac_f32_e32 v133, v96, v96
	v_add_f32_e32 v132, v132, v133
	v_add_f32_e32 v131, v132, v131
	v_mov_b32_e32 v132, v131
	s_nop 1
	v_permlane16_swap_b32_e32 v131, v132
	v_add_f32_e32 v131, v131, v132
	v_mov_b32_e32 v132, v131
	s_nop 1
	v_permlane32_swap_b32_e32 v131, v132
	s_and_saveexec_b64 s[0:1], vcc
	v_add_f32_e32 v131, v131, v132
	ds_write_b32 v130, v131 offset:256
;     __device__ __forceinline__ void operator()(f32x4 (&acc)[2][2][4][2], const Unit& u, int wr, int wc, int fr_, int fq_) const {
;     ...
;         for (int ai = 0; ai < 2; ++ai)
; #pragma unroll
;             for (int m = 0; m < 4; ++m) { float q = 0.f;
; #pragma unroll
;                 for (int bj = 0; bj < 2; ++bj)
; #pragma unroll
;                     for (int n = 0; n < 2; ++n) { const f32x4 x = acc[ai][bj][m][n]; q += (x[0] * x[0] + x[1] * x[1]) + (x[2] * x[2] + x[3] * x[3]); }
;                 { auto s_ = __builtin_amdgcn_permlane16_swap(__float_as_uint(q), __float_as_uint(q), false, false); q = __uint_as_float(s_[0]) + __uint_as_float(s_[1]); }
;                 { auto s_ = __builtin_amdgcn_permlane32_swap(__float_as_uint(q), __float_as_uint(q), false, false); q = __uint_as_float(s_[0]) + __uint_as_float(s_[1]); }
;                 if (fq == 0) P[(ai * HALF + wr * 64 + m * 16 + fr) * 4 + wc] = q; }
;         asm volatile("s_waitcnt lgkmcnt(0)" ::: "memory"); __builtin_amdgcn_s_barrier(); asm volatile("" ::: "memory");
	s_or_b64 exec, exec, s[0:1]
	v_mul_f32_e32 v131, v99, v99
	v_mul_f32_e32 v132, v101, v101
	v_fmac_f32_e32 v131, v98, v98
	v_fmac_f32_e32 v132, v100, v100
	v_add_f32_e32 v131, v131, v132
	v_mul_f32_e32 v132, v103, v103
	v_mul_f32_e32 v133, v105, v105
	v_fmac_f32_e32 v132, v102, v102
	v_fmac_f32_e32 v133, v104, v104
	v_add_f32_e32 v132, v132, v133
	v_add_f32_e32 v131, v131, v132
	v_mul_f32_e32 v132, v107, v107
	v_mul_f32_e32 v133, v109, v109
	v_fmac_f32_e32 v132, v106, v106
	v_fmac_f32_e32 v133, v108, v108
	v_add_f32_e32 v132, v132, v133
	v_add_f32_e32 v131, v132, v131
	v_mul_f32_e32 v132, v111, v111
	v_mul_f32_e32 v133, v113, v113
	v_fmac_f32_e32 v132, v110, v110
	v_fmac_f32_e32 v133, v112, v112
	v_add_f32_e32 v132, v132, v133
	v_add_f32_e32 v131, v132, v131
	v_mov_b32_e32 v132, v131
	s_nop 1
	v_permlane16_swap_b32_e32 v131, v132
	v_add_f32_e32 v131, v131, v132
	v_mov_b32_e32 v132, v131
	s_nop 1
	v_permlane32_swap_b32_e32 v131, v132
	s_and_saveexec_b64 s[0:1], vcc
	v_add_f32_e32 v131, v131, v132
	ds_write_b32 v130, v131 offset:512
	s_or_b64 exec, exec, s[0:1]
	v_mul_f32_e32 v131, v115, v115
	v_mul_f32_e32 v132, v117, v117
	v_fmac_f32_e32 v131, v114, v114
	v_fmac_f32_e32 v132, v116, v116
	v_add_f32_e32 v131, v131, v132
	v_mul_f32_e32 v132, v119, v119
	v_mul_f32_e32 v133, v121, v121
	v_fmac_f32_e32 v132, v118, v118
	v_fmac_f32_e32 v133, v120, v120
	v_add_f32_e32 v132, v132, v133
	v_add_f32_e32 v131, v131, v132
	v_mul_f32_e32 v132, v123, v123
	v_mul_f32_e32 v133, v125, v125
	v_fmac_f32_e32 v132, v122, v122
	v_fmac_f32_e32 v133, v124, v124
	v_add_f32_e32 v132, v132, v133
	v_add_f32_e32 v131, v132, v131
	v_mul_f32_e32 v132, v127, v127
	v_mul_f32_e32 v133, v129, v129
	v_fmac_f32_e32 v132, v126, v126
	v_fmac_f32_e32 v133, v128, v128
	v_add_f32_e32 v132, v132, v133
	v_add_f32_e32 v131, v132, v131
	v_mov_b32_e32 v132, v131
	s_nop 1
	v_permlane16_swap_b32_e32 v131, v132
	v_add_f32_e32 v131, v131, v132
	v_mov_b32_e32 v132, v131
	s_nop 1
	v_permlane32_swap_b32_e32 v131, v132
	s_and_saveexec_b64 s[0:1], vcc
	v_add_f32_e32 v131, v131, v132
	ds_write_b32 v130, v131 offset:768
	s_or_b64 exec, exec, s[0:1]
	v_mul_f32_e32 v131, v91, v91
	v_mul_f32_e32 v132, v93, v93
	v_fmac_f32_e32 v131, v90, v90
	v_fmac_f32_e32 v132, v92, v92
	v_add_f32_e32 v131, v131, v132
	v_mul_f32_e32 v132, v83, v83
	v_mul_f32_e32 v133, v85, v85
	v_fmac_f32_e32 v132, v82, v82
	v_fmac_f32_e32 v133, v84, v84
	v_add_f32_e32 v132, v132, v133
	v_add_f32_e32 v131, v131, v132
	v_mul_f32_e32 v132, v75, v75
	v_mul_f32_e32 v133, v77, v77
	v_fmac_f32_e32 v132, v74, v74
	v_fmac_f32_e32 v133, v76, v76
	v_add_f32_e32 v132, v132, v133
	v_add_f32_e32 v131, v132, v131
	v_mul_f32_e32 v132, v63, v63
	v_mul_f32_e32 v133, v65, v65
	v_fmac_f32_e32 v132, v62, v62
	v_fmac_f32_e32 v133, v64, v64
	v_add_f32_e32 v132, v132, v133
	v_add_f32_e32 v131, v132, v131
	v_mov_b32_e32 v132, v131
	s_nop 1
	v_permlane16_swap_b32_e32 v131, v132
	v_add_f32_e32 v131, v131, v132
	v_mov_b32_e32 v132, v131
	s_nop 1
	v_permlane32_swap_b32_e32 v131, v132
	s_and_saveexec_b64 s[0:1], vcc
	v_add_f32_e32 v131, v131, v132
	ds_write_b32 v130, v131 offset:2048
	s_or_b64 exec, exec, s[0:1]
	v_mul_f32_e32 v131, v47, v47
	v_mul_f32_e32 v132, v49, v49
	v_fmac_f32_e32 v131, v46, v46
	v_fmac_f32_e32 v132, v48, v48
	v_add_f32_e32 v131, v131, v132
	v_mul_f32_e32 v132, v43, v43
	v_mul_f32_e32 v133, v45, v45
	v_fmac_f32_e32 v132, v42, v42
	v_fmac_f32_e32 v133, v44, v44
	v_add_f32_e32 v132, v132, v133
	v_add_f32_e32 v131, v131, v132
	v_mul_f32_e32 v132, v39, v39
	v_mul_f32_e32 v133, v41, v41
	v_fmac_f32_e32 v132, v38, v38
	v_fmac_f32_e32 v133, v40, v40
	v_add_f32_e32 v132, v132, v133
	v_add_f32_e32 v131, v132, v131
	v_mul_f32_e32 v132, v35, v35
	v_mul_f32_e32 v133, v37, v37
	v_fmac_f32_e32 v132, v34, v34
	v_fmac_f32_e32 v133, v36, v36
	v_add_f32_e32 v132, v132, v133
	v_add_f32_e32 v131, v132, v131
	v_mov_b32_e32 v132, v131
	s_nop 1
	v_permlane16_swap_b32_e32 v131, v132
	v_add_f32_e32 v131, v131, v132
	v_mov_b32_e32 v132, v131
	s_nop 1
	v_permlane32_swap_b32_e32 v131, v132
	s_and_saveexec_b64 s[0:1], vcc
	v_add_f32_e32 v131, v131, v132
	ds_write_b32 v130, v131 offset:2304
	s_or_b64 exec, exec, s[0:1]
	v_mul_f32_e32 v131, v31, v31
	v_mul_f32_e32 v132, v33, v33
	v_fmac_f32_e32 v131, v30, v30
	v_fmac_f32_e32 v132, v32, v32
	v_add_f32_e32 v131, v131, v132
	v_mul_f32_e32 v132, v27, v27
	v_mul_f32_e32 v133, v29, v29
	v_fmac_f32_e32 v132, v26, v26
	v_fmac_f32_e32 v133, v28, v28
	v_add_f32_e32 v132, v132, v133
	v_add_f32_e32 v131, v131, v132
	v_mul_f32_e32 v132, v23, v23
	v_mul_f32_e32 v133, v25, v25
	v_fmac_f32_e32 v132, v22, v22
	v_fmac_f32_e32 v133, v24, v24
	v_add_f32_e32 v132, v132, v133
	v_add_f32_e32 v131, v132, v131
	v_mul_f32_e32 v132, v19, v19
	v_mul_f32_e32 v133, v21, v21
	v_fmac_f32_e32 v132, v18, v18
	v_fmac_f32_e32 v133, v20, v20
	v_add_f32_e32 v132, v132, v133
	v_add_f32_e32 v131, v132, v131
	v_mov_b32_e32 v132, v131
	s_nop 1
	v_permlane16_swap_b32_e32 v131, v132
	v_add_f32_e32 v131, v131, v132
	v_mov_b32_e32 v132, v131
	s_nop 1
	v_permlane32_swap_b32_e32 v131, v132
	s_and_saveexec_b64 s[0:1], vcc
	v_add_f32_e32 v131, v131, v132
	ds_write_b32 v130, v131 offset:2560
	s_or_b64 exec, exec, s[0:1]
	v_mul_f32_e32 v131, v15, v15
	v_mul_f32_e32 v132, v17, v17
	v_fmac_f32_e32 v131, v14, v14
	v_fmac_f32_e32 v132, v16, v16
	v_add_f32_e32 v131, v131, v132
	v_mul_f32_e32 v132, v11, v11
	v_mul_f32_e32 v133, v13, v13
	v_fmac_f32_e32 v132, v10, v10
	v_fmac_f32_e32 v133, v12, v12
	v_add_f32_e32 v132, v132, v133
	v_add_f32_e32 v131, v131, v132
	v_mul_f32_e32 v132, v7, v7
	v_mul_f32_e32 v133, v9, v9
	v_fmac_f32_e32 v132, v6, v6
	v_fmac_f32_e32 v133, v8, v8
	v_add_f32_e32 v132, v132, v133
	v_add_f32_e32 v131, v132, v131
	v_mul_f32_e32 v132, v3, v3
	v_mul_f32_e32 v133, v5, v5
	v_fmac_f32_e32 v132, v2, v2
	v_fmac_f32_e32 v133, v4, v4
	v_add_f32_e32 v132, v132, v133
	v_add_f32_e32 v131, v132, v131
	v_mov_b32_e32 v132, v131
	s_nop 1
	v_permlane16_swap_b32_e32 v131, v132
	v_add_f32_e32 v131, v131, v132
	v_mov_b32_e32 v132, v131
	s_nop 1
	v_permlane32_swap_b32_e32 v131, v132
	s_and_saveexec_b64 s[0:1], vcc
	v_add_f32_e32 v131, v131, v132
	ds_write_b32 v130, v131 offset:2816
	s_or_b64 exec, exec, s[0:1]
	s_waitcnt lgkmcnt(0)
	s_barrier
;     __device__ __forceinline__ void operator()(f32x4 (&acc)[2][2][4][2], const Unit& u, int wr, int wc, int fr_, int fq_) const {
;     ...
;         const int wid = wr * 4 + wc, lane = fq * 16 + fr, row = wid * 32 + (lane & 31);
;         if (lane < 32) { const float t = (P[row * 4 + 0] + P[row * 4 + 1]) + (P[row * 4 + 2] + P[row * 4 + 3]);
;             __hip_atomic_store(xbuf + ((size_t)u.pm * BM + row) * 8 + u.pn, t, __ATOMIC_RELAXED, __HIP_MEMORY_SCOPE_AGENT); }
	v_lshl_add_u32 v162, v183, 4, v182
	v_and_or_b32 v160, v162, 31, s53
	v_cmp_gt_i32_e64 s[8:9], 32, v162
	v_ashrrev_i32_e32 v161, 31, v160
	s_and_saveexec_b64 s[0:1], s[8:9]
	s_cbranch_execz .LBB0_1444
	v_lshl_add_u32 v130, v160, 4, 0
	v_add_u32_e32 v130, 0x20540, v130
	ds_read_b128 v[130:133], v130
	s_ashr_i32 s23, s22, 31
	s_lshl_b64 s[26:27], s[22:23], 13
	s_add_u32 s26, s35, s26
	s_addc_u32 s27, s36, s27
	s_waitcnt lgkmcnt(0)
	v_mov_b32_e32 v134, v131
	v_mov_b32_e32 v135, v132
	v_mov_b32_e32 v131, v133
	v_lshlrev_b64 v[132:133], 5, v[160:161]
	v_pk_add_f32 v[130:131], v[134:135], v[130:131]
	v_lshl_add_u64 v[132:133], s[26:27], 0, v[132:133]
	s_ashr_i32 s25, s24, 31
	v_pk_add_f32 v[130:131], v[130:131], v[130:131] op_sel:[0,1] op_sel_hi:[1,0]
	v_lshl_add_u64 v[132:133], s[24:25], 2, v[132:133]
	global_store_dword v[132:133], v130, off sc1

;     __device__ __forceinline__ void operator()(f32x4 (&acc)[2][2][4][2], const Unit& u, int wr, int wc, int fr_, int fq_) const {
;     ...
;         const int col0 = u.pn * BM + wc * 32 + 8 * fq; const float* gp = mod + (size_t)rb * NMODC + gi * DM + col0;
;         f32x4 gv[2][2];
; #pragma unroll
;         for (int bj = 0; bj < 2; ++bj)
; #pragma unroll
;             for (int n = 0; n < 2; ++n) gv[bj][n] = *(const f32x4*)(gp + bj * HALF + 4 * n) * s;
;     ...
;         } else { const bf16_t* base = (const bf16_t*)(lat ? base_lat : base_ctx) + roff;
; #pragma unroll
;             for (int ai = 0; ai < 2; ++ai) { u32x4 bw[4][2];
; #pragma unroll
;                 for (int m = 0; m < 4; ++m)
; #pragma unroll
;                     for (int bj = 0; bj < 2; ++bj) bw[m][bj] = *(const u32x4*)(base + (size_t)(ai * HALF + m * 16) * DM + bj * HALF);
; #pragma unroll
;                 for (int m = 0; m < 4; ++m)
; #pragma unroll
;                     for (int bj = 0; bj < 2; ++bj) { f32x4 b0, b1; unpack8h(bw[m][bj], b0, b1); acc[ai][bj][m][0] = b0 + gv[bj][0] * acc[ai][bj][m][0]; acc[ai][bj][m][1] = b1 + gv[bj][1] * acc[ai][bj][m][1]; }
.LBB0_1488:
	s_add_i32 s31, s34, 0xffffff80
	s_and_b64 s[36:37], s[40:41], exec
	s_cselect_b32 s44, s34, s31
	s_lshl_b32 s31, s30, 8
	s_ashr_i32 s45, s44, 31
	s_or_b32 s31, s31, s3
	v_lshlrev_b32_e32 v200, 3, v169
	s_lshl_b64 s[36:37], s[8:9], 2
	v_add_u32_e32 v146, s31, v200
	s_add_u32 s8, s43, s36
	s_addc_u32 s9, s50, s37
	v_ashrrev_i32_e32 v147, 31, v146
	v_lshl_add_u64 v[130:131], v[146:147], 2, s[8:9]
	s_mov_b64 s[8:9], 0x110000
	v_lshl_add_u64 v[138:139], v[130:131], 0, s[8:9]
	s_mov_b32 s8, 0x110000
	v_add_co_u32_e32 v130, vcc, s8, v130
	v_add_u32_e32 v198, s2, v168
	s_nop 0
	v_addc_co_u32_e32 v131, vcc, 0, v131, vcc
	global_load_dwordx4 v[130:133], v[130:131], off
	s_nop 0
	global_load_dwordx4 v[134:137], v[138:139], off offset:16
	v_ashrrev_i32_e32 v199, 31, v198
	s_lshl_b64 s[8:9], s[44:45], 19
	global_load_dwordx4 v[220:223], v[138:139], off offset:528
	global_load_dwordx4 v[224:227], v[138:139], off offset:512
	v_lshlrev_b64 v[228:229], 11, v[198:199]
	v_lshl_add_u64 v[228:229], v[228:229], 0, s[8:9]
	v_lshl_add_u64 v[148:149], v[228:229], 0, v[146:147]
	v_lshl_add_u64 v[166:167], v[148:149], 1, s[0:1]
	global_load_dwordx4 v[170:173], v[166:167], off
	global_load_dwordx4 v[174:177], v[166:167], off offset:256
	v_add_co_u32_e32 v228, vcc, s80, v166
	s_nop 1
	v_addc_co_u32_e32 v229, vcc, 0, v167, vcc
	global_load_dwordx4 v[208:211], v[228:229], off
	global_load_dwordx4 v[212:215], v[228:229], off offset:256
	v_add_co_u32_e32 v228, vcc, s75, v166
	s_nop 1
	v_addc_co_u32_e32 v229, vcc, 0, v167, vcc
	global_load_dwordx4 v[142:145], v[228:229], off
	global_load_dwordx4 v[138:141], v[228:229], off offset:256
	s_waitcnt vmcnt(6)
	v_pk_mul_f32 v[164:165], v[132:133], 0.5 op_sel_hi:[1,0]
	v_pk_mul_f32 v[162:163], v[130:131], 0.5 op_sel_hi:[1,0]
	v_pk_mul_f32 v[160:161], v[136:137], 0.5 op_sel_hi:[1,0]
	v_pk_mul_f32 v[158:159], v[134:135], 0.5 op_sel_hi:[1,0]
	v_pk_mul_f32 v[150:151], v[220:221], 0.5 op_sel_hi:[1,0]
	v_pk_mul_f32 v[156:157], v[226:227], 0.5 op_sel_hi:[1,0]
	v_pk_mul_f32 v[154:155], v[224:225], 0.5 op_sel_hi:[1,0]
	v_pk_mul_f32 v[152:153], v[222:223], 0.5 op_sel_hi:[1,0]
	v_add_co_u32_e32 v130, vcc, s82, v166
	s_nop 1
	v_addc_co_u32_e32 v131, vcc, 0, v167, vcc
	global_load_dwordx4 v[134:137], v[130:131], off
	s_nop 0
	global_load_dwordx4 v[130:133], v[130:131], off offset:256
	s_mov_b32 s0, 0x90000
	s_waitcnt vmcnt(7)
	v_cvt_f32_f16_e32 v188, v172
	v_cvt_f32_f16_sdwa v189, v172 dst_sel:DWORD dst_unused:UNUSED_PAD src0_sel:WORD_1
	v_cvt_f32_f16_e32 v172, v173
	v_cvt_f32_f16_sdwa v173, v173 dst_sel:DWORD dst_unused:UNUSED_PAD src0_sel:WORD_1
	v_cvt_f32_f16_e32 v190, v170
	v_cvt_f32_f16_sdwa v191, v170 dst_sel:DWORD dst_unused:UNUSED_PAD src0_sel:WORD_1
	v_cvt_f32_f16_e32 v170, v171
	v_cvt_f32_f16_sdwa v171, v171 dst_sel:DWORD dst_unused:UNUSED_PAD src0_sel:WORD_1
	v_pk_fma_f32 v[24:25], v[24:25], v[160:161], v[172:173]
	s_waitcnt vmcnt(6)
	v_cvt_f32_f16_e32 v172, v177
	v_cvt_f32_f16_sdwa v173, v177 dst_sel:DWORD dst_unused:UNUSED_PAD src0_sel:WORD_1
	v_pk_fma_f32 v[32:33], v[32:33], v[164:165], v[170:171]
	v_cvt_f32_f16_e32 v170, v176
	v_cvt_f32_f16_sdwa v171, v176 dst_sel:DWORD dst_unused:UNUSED_PAD src0_sel:WORD_1
	v_pk_fma_f32 v[16:17], v[16:17], v[152:153], v[172:173]
	s_waitcnt vmcnt(5)
	v_cvt_f32_f16_e32 v172, v211
	v_cvt_f32_f16_sdwa v173, v211 dst_sel:DWORD dst_unused:UNUSED_PAD src0_sel:WORD_1
	v_pk_fma_f32 v[14:15], v[14:15], v[150:151], v[170:171]
	v_cvt_f32_f16_e32 v170, v210
	v_cvt_f32_f16_sdwa v171, v210 dst_sel:DWORD dst_unused:UNUSED_PAD src0_sel:WORD_1
	v_pk_fma_f32 v[12:13], v[12:13], v[160:161], v[172:173]
	s_waitcnt vmcnt(4)
	v_cvt_f32_f16_e32 v172, v215
	v_cvt_f32_f16_sdwa v173, v215 dst_sel:DWORD dst_unused:UNUSED_PAD src0_sel:WORD_1
	v_pk_fma_f32 v[10:11], v[10:11], v[158:159], v[170:171]
	v_cvt_f32_f16_e32 v170, v214
	v_cvt_f32_f16_sdwa v171, v214 dst_sel:DWORD dst_unused:UNUSED_PAD src0_sel:WORD_1
	v_pk_fma_f32 v[48:49], v[48:49], v[152:153], v[172:173]
	s_waitcnt vmcnt(3)
	v_cvt_f32_f16_e32 v172, v142
	v_cvt_f32_f16_sdwa v173, v142 dst_sel:DWORD dst_unused:UNUSED_PAD src0_sel:WORD_1
	v_pk_fma_f32 v[46:47], v[46:47], v[150:151], v[170:171]
	v_cvt_f32_f16_e32 v170, v144
	v_cvt_f32_f16_sdwa v171, v144 dst_sel:DWORD dst_unused:UNUSED_PAD src0_sel:WORD_1
	v_cvt_f32_f16_e32 v144, v145
	v_cvt_f32_f16_sdwa v145, v145 dst_sel:DWORD dst_unused:UNUSED_PAD src0_sel:WORD_1
	v_cvt_f32_f16_e32 v142, v143
	v_cvt_f32_f16_sdwa v143, v143 dst_sel:DWORD dst_unused:UNUSED_PAD src0_sel:WORD_1
	v_cvt_f32_f16_e32 v176, v174
	v_cvt_f32_f16_sdwa v177, v174 dst_sel:DWORD dst_unused:UNUSED_PAD src0_sel:WORD_1
	v_cvt_f32_f16_e32 v174, v175
	v_cvt_f32_f16_sdwa v175, v175 dst_sel:DWORD dst_unused:UNUSED_PAD src0_sel:WORD_1
	v_pk_fma_f32 v[52:53], v[52:53], v[164:165], v[142:143]
	v_pk_fma_f32 v[56:57], v[56:57], v[160:161], v[144:145]
	s_waitcnt vmcnt(2)
	v_cvt_f32_f16_e32 v142, v140
	v_cvt_f32_f16_sdwa v143, v140 dst_sel:DWORD dst_unused:UNUSED_PAD src0_sel:WORD_1
	v_cvt_f32_f16_e32 v140, v141
	v_cvt_f32_f16_sdwa v141, v141 dst_sel:DWORD dst_unused:UNUSED_PAD src0_sel:WORD_1
	v_cvt_f32_f16_e32 v144, v138
	v_cvt_f32_f16_sdwa v145, v138 dst_sel:DWORD dst_unused:UNUSED_PAD src0_sel:WORD_1
	v_cvt_f32_f16_e32 v138, v139
	v_cvt_f32_f16_sdwa v139, v139 dst_sel:DWORD dst_unused:UNUSED_PAD src0_sel:WORD_1
	v_pk_fma_f32 v[28:29], v[28:29], v[156:157], v[174:175]
	v_pk_fma_f32 v[26:27], v[26:27], v[154:155], v[176:177]
	v_cvt_f32_f16_e32 v174, v208
	v_cvt_f32_f16_sdwa v175, v208 dst_sel:DWORD dst_unused:UNUSED_PAD src0_sel:WORD_1
	v_cvt_f32_f16_e32 v176, v209
	v_cvt_f32_f16_sdwa v177, v209 dst_sel:DWORD dst_unused:UNUSED_PAD src0_sel:WORD_1
	v_pk_fma_f32 v[68:69], v[68:69], v[156:157], v[138:139]
	v_pk_fma_f32 v[72:73], v[72:73], v[152:153], v[140:141]
	s_waitcnt vmcnt(1)
;     __device__ __forceinline__ void operator()(f32x4 (&acc)[2][2][4][2], const Unit& u, int wr, int wc, int fr_, int fq_) const {
;     ...
;             for (int ai = 0; ai < 2; ++ai) { u32x4 bw[4][2];
; #pragma unroll
;                 for (int m = 0; m < 4; ++m)
; #pragma unroll
;                     for (int bj = 0; bj < 2; ++bj) bw[m][bj] = *(const u32x4*)(base + (size_t)(ai * HALF + m * 16) * DM + bj * HALF);
; #pragma unroll
;                 for (int m = 0; m < 4; ++m)
; #pragma unroll
;                     for (int bj = 0; bj < 2; ++bj) { f32x4 b0, b1; unpack8h(bw[m][bj], b0, b1); acc[ai][bj][m][0] = b0 + gv[bj][0] * acc[ai][bj][m][0]; acc[ai][bj][m][1] = b1 + gv[bj][1] * acc[ai][bj][m][1]; }
	v_cvt_f32_f16_e32 v138, v136
	v_cvt_f32_f16_sdwa v139, v136 dst_sel:DWORD dst_unused:UNUSED_PAD src0_sel:WORD_1
	v_cvt_f32_f16_e32 v136, v137
	v_cvt_f32_f16_sdwa v137, v137 dst_sel:DWORD dst_unused:UNUSED_PAD src0_sel:WORD_1
	v_cvt_f32_f16_e32 v140, v134
	v_cvt_f32_f16_sdwa v141, v134 dst_sel:DWORD dst_unused:UNUSED_PAD src0_sel:WORD_1
	v_cvt_f32_f16_e32 v134, v135
	v_cvt_f32_f16_sdwa v135, v135 dst_sel:DWORD dst_unused:UNUSED_PAD src0_sel:WORD_1
	v_pk_fma_f32 v[20:21], v[20:21], v[164:165], v[176:177]
	v_pk_fma_f32 v[18:19], v[18:19], v[162:163], v[174:175]
	v_cvt_f32_f16_e32 v174, v212
	v_cvt_f32_f16_sdwa v175, v212 dst_sel:DWORD dst_unused:UNUSED_PAD src0_sel:WORD_1
	v_cvt_f32_f16_e32 v176, v213
	v_cvt_f32_f16_sdwa v177, v213 dst_sel:DWORD dst_unused:UNUSED_PAD src0_sel:WORD_1
	v_pk_fma_f32 v[76:77], v[76:77], v[164:165], v[134:135]
	v_pk_fma_f32 v[80:81], v[80:81], v[160:161], v[136:137]
	s_waitcnt vmcnt(0)
	v_cvt_f32_f16_e32 v134, v132
	v_cvt_f32_f16_sdwa v135, v132 dst_sel:DWORD dst_unused:UNUSED_PAD src0_sel:WORD_1
	v_cvt_f32_f16_e32 v132, v133
	v_cvt_f32_f16_sdwa v133, v133 dst_sel:DWORD dst_unused:UNUSED_PAD src0_sel:WORD_1
	v_cvt_f32_f16_e32 v136, v130
	v_cvt_f32_f16_sdwa v137, v130 dst_sel:DWORD dst_unused:UNUSED_PAD src0_sel:WORD_1
	v_cvt_f32_f16_e32 v130, v131
	v_cvt_f32_f16_sdwa v131, v131 dst_sel:DWORD dst_unused:UNUSED_PAD src0_sel:WORD_1
	v_pk_fma_f32 v[30:31], v[30:31], v[162:163], v[190:191]
	v_pk_fma_f32 v[22:23], v[22:23], v[158:159], v[188:189]
	v_pk_fma_f32 v[44:45], v[44:45], v[156:157], v[176:177]
	v_pk_fma_f32 v[42:43], v[42:43], v[154:155], v[174:175]
	v_pk_fma_f32 v[50:51], v[50:51], v[162:163], v[172:173]
	v_pk_fma_f32 v[54:55], v[54:55], v[158:159], v[170:171]
	v_pk_fma_f32 v[66:67], v[66:67], v[154:155], v[144:145]
	v_pk_fma_f32 v[70:71], v[70:71], v[150:151], v[142:143]
	v_pk_fma_f32 v[74:75], v[74:75], v[162:163], v[140:141]
	v_pk_fma_f32 v[78:79], v[78:79], v[158:159], v[138:139]
	v_pk_fma_f32 v[84:85], v[84:85], v[156:157], v[130:131]
	v_pk_fma_f32 v[82:83], v[82:83], v[154:155], v[136:137]
	v_pk_fma_f32 v[88:89], v[88:89], v[152:153], v[132:133]
	v_pk_fma_f32 v[86:87], v[86:87], v[150:151], v[134:135]
	v_add_co_u32_e32 v130, vcc, s52, v166
	s_nop 1
	v_addc_co_u32_e32 v131, vcc, 0, v167, vcc
	global_load_dwordx4 v[142:145], v[130:131], off
	global_load_dwordx4 v[170:173], v[130:131], off offset:256
	v_add_co_u32_e32 v130, vcc, s0, v166
	s_mov_b32 s0, 0xa0000
	s_nop 0
	v_addc_co_u32_e32 v131, vcc, 0, v167, vcc
	global_load_dwordx4 v[174:177], v[130:131], off
	global_load_dwordx4 v[208:211], v[130:131], off offset:256
	v_add_co_u32_e32 v130, vcc, s0, v166
	s_mov_b32 s0, 0xb0000
	s_nop 0
	v_addc_co_u32_e32 v131, vcc, 0, v167, vcc
	global_load_dwordx4 v[212:215], v[130:131], off
	global_load_dwordx4 v[138:141], v[130:131], off offset:256
	v_add_co_u32_e32 v130, vcc, s0, v166
	s_waitcnt vmcnt(5)
	v_cvt_f32_f16_e32 v166, v144
	v_addc_co_u32_e32 v131, vcc, 0, v167, vcc
	global_load_dwordx4 v[134:137], v[130:131], off
	s_nop 0
	global_load_dwordx4 v[130:133], v[130:131], off offset:256
	v_cvt_f32_f16_sdwa v167, v144 dst_sel:DWORD dst_unused:UNUSED_PAD src0_sel:WORD_1
	v_cvt_f32_f16_e32 v144, v145
	v_cvt_f32_f16_sdwa v145, v145 dst_sel:DWORD dst_unused:UNUSED_PAD src0_sel:WORD_1
	v_cvt_f32_f16_e32 v188, v142
	v_cvt_f32_f16_sdwa v189, v142 dst_sel:DWORD dst_unused:UNUSED_PAD src0_sel:WORD_1
	v_cvt_f32_f16_e32 v142, v143
	v_cvt_f32_f16_sdwa v143, v143 dst_sel:DWORD dst_unused:UNUSED_PAD src0_sel:WORD_1
	v_pk_fma_f32 v[112:113], v[112:113], v[160:161], v[144:145]
	s_waitcnt vmcnt(6)
	v_cvt_f32_f16_e32 v144, v173
	v_cvt_f32_f16_sdwa v145, v173 dst_sel:DWORD dst_unused:UNUSED_PAD src0_sel:WORD_1
	v_pk_fma_f32 v[108:109], v[108:109], v[164:165], v[142:143]
	v_cvt_f32_f16_e32 v142, v172
	v_cvt_f32_f16_sdwa v143, v172 dst_sel:DWORD dst_unused:UNUSED_PAD src0_sel:WORD_1
	v_pk_fma_f32 v[120:121], v[120:121], v[152:153], v[144:145]
	s_waitcnt vmcnt(5)
	v_cvt_f32_f16_e32 v144, v177
	v_cvt_f32_f16_sdwa v145, v177 dst_sel:DWORD dst_unused:UNUSED_PAD src0_sel:WORD_1
	v_pk_fma_f32 v[118:119], v[118:119], v[150:151], v[142:143]
	v_cvt_f32_f16_e32 v142, v176
	v_cvt_f32_f16_sdwa v143, v176 dst_sel:DWORD dst_unused:UNUSED_PAD src0_sel:WORD_1
	v_pk_fma_f32 v[128:129], v[128:129], v[160:161], v[144:145]
	s_waitcnt vmcnt(4)
	v_cvt_f32_f16_e32 v144, v211
	v_cvt_f32_f16_sdwa v145, v211 dst_sel:DWORD dst_unused:UNUSED_PAD src0_sel:WORD_1
	v_pk_fma_f32 v[126:127], v[126:127], v[158:159], v[142:143]
	v_cvt_f32_f16_e32 v142, v210
	v_cvt_f32_f16_sdwa v143, v210 dst_sel:DWORD dst_unused:UNUSED_PAD src0_sel:WORD_1
	v_pk_fma_f32 v[100:101], v[100:101], v[152:153], v[144:145]
	s_waitcnt vmcnt(3)
	v_cvt_f32_f16_e32 v144, v215
	v_cvt_f32_f16_sdwa v145, v215 dst_sel:DWORD dst_unused:UNUSED_PAD src0_sel:WORD_1
	v_pk_fma_f32 v[98:99], v[98:99], v[150:151], v[142:143]
	v_cvt_f32_f16_e32 v142, v214
	v_cvt_f32_f16_sdwa v143, v214 dst_sel:DWORD dst_unused:UNUSED_PAD src0_sel:WORD_1
	v_pk_fma_f32 v[92:93], v[92:93], v[160:161], v[144:145]
	s_waitcnt vmcnt(2)
; #define PG8_LAS __attribute__((address_space(3)))
;     __device__ __forceinline__ void operator()(f32x4 (&acc)[2][2][4][2], const Unit& u, int wr, int wc, int fr_, int fq_) const {
;     ...
;                 for (int m = 0; m < 4; ++m)
; #pragma unroll
;                     for (int bj = 0; bj < 2; ++bj) { f32x4 b0, b1; unpack8h(bw[m][bj], b0, b1); acc[ai][bj][m][0] = b0 + gv[bj][0] * acc[ai][bj][m][0]; acc[ai][bj][m][1] = b1 + gv[bj][1] * acc[ai][bj][m][1]; }
;                 asm volatile("" : "+v"(acc[ai][0][0][0]), "+v"(acc[ai][0][0][1]), "+v"(acc[ai][1][0][0]), "+v"(acc[ai][1][0][1]), "+v"(acc[ai][0][1][0]), "+v"(acc[ai][0][1][1]), "+v"(acc[ai][1][1][0]), "+v"(acc[ai][1][1][1]),
;                                   "+v"(acc[ai][0][2][0]), "+v"(acc[ai][0][2][1]), "+v"(acc[ai][1][2][0]), "+v"(acc[ai][1][2][1]), "+v"(acc[ai][0][3][0]), "+v"(acc[ai][0][3][1]), "+v"(acc[ai][1][3][0]), "+v"(acc[ai][1][3][1]) :: "memory"); }
;         }
;         PG8_LAS float* P = (PG8_LAS float*)xl; PG8_LAS float* S = P + 1024;
; #pragma unroll
;         for (int ai = 0; ai < 2; ++ai)
; #pragma unroll
;             for (int m = 0; m < 4; ++m) { float q = 0.f;
; #pragma unroll
;                 for (int bj = 0; bj < 2; ++bj)
; #pragma unroll
;                     for (int n = 0; n < 2; ++n) { const f32x4 x = acc[ai][bj][m][n]; q += (x[0] * x[0] + x[1] * x[1]) + (x[2] * x[2] + x[3] * x[3]); }
;                 { auto s_ = __builtin_amdgcn_permlane16_swap(__float_as_uint(q), __float_as_uint(q), false, false); q = __uint_as_float(s_[0]) + __uint_as_float(s_[1]); }
;                 { auto s_ = __builtin_amdgcn_permlane32_swap(__float_as_uint(q), __float_as_uint(q), false, false); q = __uint_as_float(s_[0]) + __uint_as_float(s_[1]); }
;                 if (fq == 0) P[(ai * HALF + wr * 64 + m * 16 + fr) * 4 + wc] = q; }
	v_cvt_f32_f16_e32 v144, v138
	v_cvt_f32_f16_sdwa v145, v138 dst_sel:DWORD dst_unused:UNUSED_PAD src0_sel:WORD_1
	v_cvt_f32_f16_e32 v138, v139
	v_cvt_f32_f16_sdwa v139, v139 dst_sel:DWORD dst_unused:UNUSED_PAD src0_sel:WORD_1
	v_pk_fma_f32 v[90:91], v[90:91], v[158:159], v[142:143]
	v_cvt_f32_f16_e32 v142, v140
	v_cvt_f32_f16_sdwa v143, v140 dst_sel:DWORD dst_unused:UNUSED_PAD src0_sel:WORD_1
	v_cvt_f32_f16_e32 v140, v141
	v_cvt_f32_f16_sdwa v141, v141 dst_sel:DWORD dst_unused:UNUSED_PAD src0_sel:WORD_1
	v_pk_fma_f32 v[64:65], v[64:65], v[156:157], v[138:139]
	v_pk_fma_f32 v[110:111], v[110:111], v[158:159], v[166:167]
	v_cvt_f32_f16_e32 v166, v170
	v_pk_fma_f32 v[60:61], v[60:61], v[152:153], v[140:141]
	v_cvt_f32_f16_sdwa v167, v170 dst_sel:DWORD dst_unused:UNUSED_PAD src0_sel:WORD_1
	v_cvt_f32_f16_e32 v170, v171
	v_cvt_f32_f16_sdwa v171, v171 dst_sel:DWORD dst_unused:UNUSED_PAD src0_sel:WORD_1
	v_pk_fma_f32 v[106:107], v[106:107], v[162:163], v[188:189]
	v_pk_fma_f32 v[114:115], v[114:115], v[154:155], v[166:167]
	v_cvt_f32_f16_e32 v166, v174
	v_pk_fma_f32 v[116:117], v[116:117], v[156:157], v[170:171]
	v_cvt_f32_f16_sdwa v167, v174 dst_sel:DWORD dst_unused:UNUSED_PAD src0_sel:WORD_1
	v_cvt_f32_f16_e32 v170, v175
	v_cvt_f32_f16_sdwa v171, v175 dst_sel:DWORD dst_unused:UNUSED_PAD src0_sel:WORD_1
	v_pk_fma_f32 v[62:63], v[62:63], v[154:155], v[144:145]
	v_pk_fma_f32 v[122:123], v[122:123], v[162:163], v[166:167]
	v_cvt_f32_f16_e32 v166, v208
	v_pk_fma_f32 v[124:125], v[124:125], v[164:165], v[170:171]
	v_cvt_f32_f16_sdwa v167, v208 dst_sel:DWORD dst_unused:UNUSED_PAD src0_sel:WORD_1
	v_cvt_f32_f16_e32 v170, v209
	v_cvt_f32_f16_sdwa v171, v209 dst_sel:DWORD dst_unused:UNUSED_PAD src0_sel:WORD_1
	v_pk_fma_f32 v[58:59], v[58:59], v[150:151], v[142:143]
	v_pk_fma_f32 v[102:103], v[102:103], v[154:155], v[166:167]
	v_cvt_f32_f16_e32 v166, v212
	v_pk_fma_f32 v[104:105], v[104:105], v[156:157], v[170:171]
	v_cvt_f32_f16_sdwa v167, v212 dst_sel:DWORD dst_unused:UNUSED_PAD src0_sel:WORD_1
	v_cvt_f32_f16_e32 v170, v213
	v_cvt_f32_f16_sdwa v171, v213 dst_sel:DWORD dst_unused:UNUSED_PAD src0_sel:WORD_1
	v_cmp_eq_u32_e32 vcc, 0, v169
	v_pk_fma_f32 v[94:95], v[94:95], v[162:163], v[166:167]
	v_pk_fma_f32 v[96:97], v[96:97], v[164:165], v[170:171]
	s_waitcnt vmcnt(1)
	v_cvt_f32_f16_e32 v138, v136
	v_cvt_f32_f16_sdwa v139, v136 dst_sel:DWORD dst_unused:UNUSED_PAD src0_sel:WORD_1
	v_cvt_f32_f16_e32 v136, v137
	v_cvt_f32_f16_sdwa v137, v137 dst_sel:DWORD dst_unused:UNUSED_PAD src0_sel:WORD_1
	v_cvt_f32_f16_e32 v140, v134
	v_cvt_f32_f16_sdwa v141, v134 dst_sel:DWORD dst_unused:UNUSED_PAD src0_sel:WORD_1
	v_cvt_f32_f16_e32 v134, v135
	v_cvt_f32_f16_sdwa v135, v135 dst_sel:DWORD dst_unused:UNUSED_PAD src0_sel:WORD_1
	v_pk_fma_f32 v[36:37], v[36:37], v[160:161], v[136:137]
	s_waitcnt vmcnt(0)
	v_cvt_f32_f16_e32 v136, v130
	v_cvt_f32_f16_sdwa v137, v130 dst_sel:DWORD dst_unused:UNUSED_PAD src0_sel:WORD_1
	v_cvt_f32_f16_e32 v130, v131
	v_cvt_f32_f16_sdwa v131, v131 dst_sel:DWORD dst_unused:UNUSED_PAD src0_sel:WORD_1
	v_pk_fma_f32 v[40:41], v[40:41], v[164:165], v[134:135]
	v_cvt_f32_f16_e32 v134, v132
	v_cvt_f32_f16_sdwa v135, v132 dst_sel:DWORD dst_unused:UNUSED_PAD src0_sel:WORD_1
	v_cvt_f32_f16_e32 v132, v133
	v_cvt_f32_f16_sdwa v133, v133 dst_sel:DWORD dst_unused:UNUSED_PAD src0_sel:WORD_1
	v_pk_fma_f32 v[8:9], v[8:9], v[156:157], v[130:131]
	v_mul_f32_e32 v130, v31, v31
	v_mul_f32_e32 v131, v33, v33
	v_fmac_f32_e32 v130, v30, v30
	v_fmac_f32_e32 v131, v32, v32
	v_pk_fma_f32 v[4:5], v[4:5], v[152:153], v[132:133]
	v_add_f32_e32 v130, v130, v131
	v_mul_f32_e32 v131, v23, v23
	v_mul_f32_e32 v132, v25, v25
	v_fmac_f32_e32 v131, v22, v22
	v_fmac_f32_e32 v132, v24, v24
	v_add_f32_e32 v131, v131, v132
	v_add_f32_e32 v130, v130, v131
	v_mul_f32_e32 v131, v27, v27
	v_mul_f32_e32 v132, v29, v29
	v_fmac_f32_e32 v131, v26, v26
	v_fmac_f32_e32 v132, v28, v28
	v_add_f32_e32 v131, v131, v132
	v_add_f32_e32 v130, v131, v130
	v_mul_f32_e32 v131, v15, v15
	v_mul_f32_e32 v132, v17, v17
	v_fmac_f32_e32 v131, v14, v14
	v_fmac_f32_e32 v132, v16, v16
	v_add_f32_e32 v131, v131, v132
	v_add_f32_e32 v130, v131, v130
	v_mov_b32_e32 v131, v130
	v_pk_fma_f32 v[38:39], v[38:39], v[162:163], v[140:141]
	v_pk_fma_f32 v[34:35], v[34:35], v[158:159], v[138:139]
	v_pk_fma_f32 v[6:7], v[6:7], v[154:155], v[136:137]
	v_pk_fma_f32 v[2:3], v[2:3], v[150:151], v[134:135]
	v_permlane16_swap_b32_e32 v130, v131
	v_add_f32_e32 v131, v130, v131
	v_mov_b32_e32 v132, v131
	s_nop 1
	v_permlane32_swap_b32_e32 v131, v132
	v_lshl_add_u32 v130, v198, 4, s88
	s_and_saveexec_b64 s[0:1], vcc
	v_add_f32_e32 v131, v131, v132
	ds_write_b32 v130, v131
	s_or_b64 exec, exec, s[0:1]
	v_mul_f32_e32 v131, v19, v19
	v_mul_f32_e32 v132, v21, v21
	v_fmac_f32_e32 v131, v18, v18
	v_fmac_f32_e32 v132, v20, v20
	v_add_f32_e32 v131, v131, v132
	v_mul_f32_e32 v132, v11, v11
	v_mul_f32_e32 v133, v13, v13
	v_fmac_f32_e32 v132, v10, v10
	v_fmac_f32_e32 v133, v12, v12
	v_add_f32_e32 v132, v132, v133
	v_add_f32_e32 v131, v131, v132
	v_mul_f32_e32 v132, v43, v43
	v_mul_f32_e32 v133, v45, v45
	v_fmac_f32_e32 v132, v42, v42
	v_fmac_f32_e32 v133, v44, v44
	v_add_f32_e32 v132, v132, v133
	v_add_f32_e32 v131, v132, v131
	v_mul_f32_e32 v132, v47, v47
	v_mul_f32_e32 v133, v49, v49
	v_fmac_f32_e32 v132, v46, v46
	v_fmac_f32_e32 v133, v48, v48
	v_add_f32_e32 v132, v132, v133
	v_add_f32_e32 v131, v132, v131
	v_mov_b32_e32 v132, v131
	s_nop 1
	v_permlane16_swap_b32_e32 v131, v132
	v_add_f32_e32 v131, v131, v132
	v_mov_b32_e32 v132, v131
	s_nop 1
	v_permlane32_swap_b32_e32 v131, v132
	s_and_saveexec_b64 s[0:1], vcc
	v_add_f32_e32 v131, v131, v132
;     __device__ __forceinline__ void operator()(f32x4 (&acc)[2][2][4][2], const Unit& u, int wr, int wc, int fr_, int fq_) const {
;     ...
;         for (int ai = 0; ai < 2; ++ai)
; #pragma unroll
;             for (int m = 0; m < 4; ++m) { float q = 0.f;
; #pragma unroll
;                 for (int bj = 0; bj < 2; ++bj)
; #pragma unroll
;                     for (int n = 0; n < 2; ++n) { const f32x4 x = acc[ai][bj][m][n]; q += (x[0] * x[0] + x[1] * x[1]) + (x[2] * x[2] + x[3] * x[3]); }
;                 { auto s_ = __builtin_amdgcn_permlane16_swap(__float_as_uint(q), __float_as_uint(q), false, false); q = __uint_as_float(s_[0]) + __uint_as_float(s_[1]); }
;                 { auto s_ = __builtin_amdgcn_permlane32_swap(__float_as_uint(q), __float_as_uint(q), false, false); q = __uint_as_float(s_[0]) + __uint_as_float(s_[1]); }
;                 if (fq == 0) P[(ai * HALF + wr * 64 + m * 16 + fr) * 4 + wc] = q; }
;         asm volatile("s_waitcnt lgkmcnt(0)" ::: "memory"); __builtin_amdgcn_s_barrier(); asm volatile("" ::: "memory");
	ds_write_b32 v130, v131 offset:256
	s_or_b64 exec, exec, s[0:1]
	v_mul_f32_e32 v131, v51, v51
	v_mul_f32_e32 v132, v53, v53
	v_fmac_f32_e32 v131, v50, v50
	v_fmac_f32_e32 v132, v52, v52
	v_add_f32_e32 v131, v131, v132
	v_mul_f32_e32 v132, v55, v55
	v_mul_f32_e32 v133, v57, v57
	v_fmac_f32_e32 v132, v54, v54
	v_fmac_f32_e32 v133, v56, v56
	v_add_f32_e32 v132, v132, v133
	v_add_f32_e32 v131, v131, v132
	v_mul_f32_e32 v132, v67, v67
	v_mul_f32_e32 v133, v69, v69
	v_fmac_f32_e32 v132, v66, v66
	v_fmac_f32_e32 v133, v68, v68
	v_add_f32_e32 v132, v132, v133
	v_add_f32_e32 v131, v132, v131
	v_mul_f32_e32 v132, v71, v71
	v_mul_f32_e32 v133, v73, v73
	v_fmac_f32_e32 v132, v70, v70
	v_fmac_f32_e32 v133, v72, v72
	v_add_f32_e32 v132, v132, v133
	v_add_f32_e32 v131, v132, v131
	v_mov_b32_e32 v132, v131
	s_nop 1
	v_permlane16_swap_b32_e32 v131, v132
	v_add_f32_e32 v131, v131, v132
	v_mov_b32_e32 v132, v131
	s_nop 1
	v_permlane32_swap_b32_e32 v131, v132
	s_and_saveexec_b64 s[0:1], vcc
	v_add_f32_e32 v131, v131, v132
	ds_write_b32 v130, v131 offset:512
	s_or_b64 exec, exec, s[0:1]
	v_mul_f32_e32 v131, v75, v75
	v_mul_f32_e32 v132, v77, v77
	v_fmac_f32_e32 v131, v74, v74
	v_fmac_f32_e32 v132, v76, v76
	v_add_f32_e32 v131, v131, v132
	v_mul_f32_e32 v132, v79, v79
	v_mul_f32_e32 v133, v81, v81
	v_fmac_f32_e32 v132, v78, v78
	v_fmac_f32_e32 v133, v80, v80
	v_add_f32_e32 v132, v132, v133
	v_add_f32_e32 v131, v131, v132
	v_mul_f32_e32 v132, v83, v83
	v_mul_f32_e32 v133, v85, v85
	v_fmac_f32_e32 v132, v82, v82
	v_fmac_f32_e32 v133, v84, v84
	v_add_f32_e32 v132, v132, v133
	v_add_f32_e32 v131, v132, v131
	v_mul_f32_e32 v132, v87, v87
	v_mul_f32_e32 v133, v89, v89
	v_fmac_f32_e32 v132, v86, v86
	v_fmac_f32_e32 v133, v88, v88
	v_add_f32_e32 v132, v132, v133
	v_add_f32_e32 v131, v132, v131
	v_mov_b32_e32 v132, v131
	s_nop 1
	v_permlane16_swap_b32_e32 v131, v132
	v_add_f32_e32 v131, v131, v132
	v_mov_b32_e32 v132, v131
	s_nop 1
	v_permlane32_swap_b32_e32 v131, v132
	s_and_saveexec_b64 s[0:1], vcc
	v_add_f32_e32 v131, v131, v132
	ds_write_b32 v130, v131 offset:768
	s_or_b64 exec, exec, s[0:1]
	v_mul_f32_e32 v131, v107, v107
	v_mul_f32_e32 v132, v109, v109
	v_fmac_f32_e32 v131, v106, v106
	v_fmac_f32_e32 v132, v108, v108
	v_add_f32_e32 v131, v131, v132
	v_mul_f32_e32 v132, v111, v111
	v_mul_f32_e32 v133, v113, v113
	v_fmac_f32_e32 v132, v110, v110
	v_fmac_f32_e32 v133, v112, v112
	v_add_f32_e32 v132, v132, v133
	v_add_f32_e32 v131, v131, v132
	v_mul_f32_e32 v132, v115, v115
	v_mul_f32_e32 v133, v117, v117
	v_fmac_f32_e32 v132, v114, v114
	v_fmac_f32_e32 v133, v116, v116
	v_add_f32_e32 v132, v132, v133
	v_add_f32_e32 v131, v132, v131
	v_mul_f32_e32 v132, v119, v119
	v_mul_f32_e32 v133, v121, v121
	v_fmac_f32_e32 v132, v118, v118
	v_fmac_f32_e32 v133, v120, v120
	v_add_f32_e32 v132, v132, v133
	v_add_f32_e32 v131, v132, v131
	v_mov_b32_e32 v132, v131
	s_nop 1
	v_permlane16_swap_b32_e32 v131, v132
	v_add_f32_e32 v131, v131, v132
	v_mov_b32_e32 v132, v131
	s_nop 1
	v_permlane32_swap_b32_e32 v131, v132
	s_and_saveexec_b64 s[0:1], vcc
	v_add_f32_e32 v131, v131, v132
	ds_write_b32 v130, v131 offset:2048
	s_or_b64 exec, exec, s[0:1]
	v_mul_f32_e32 v131, v123, v123
	v_mul_f32_e32 v132, v125, v125
	v_fmac_f32_e32 v131, v122, v122
	v_fmac_f32_e32 v132, v124, v124
	v_add_f32_e32 v131, v131, v132
	v_mul_f32_e32 v132, v127, v127
	v_mul_f32_e32 v133, v129, v129
	v_fmac_f32_e32 v132, v126, v126
	v_fmac_f32_e32 v133, v128, v128
	v_add_f32_e32 v132, v132, v133
	v_add_f32_e32 v131, v131, v132
	v_mul_f32_e32 v132, v103, v103
	v_mul_f32_e32 v133, v105, v105
	v_fmac_f32_e32 v132, v102, v102
	v_fmac_f32_e32 v133, v104, v104
	v_add_f32_e32 v132, v132, v133
	v_add_f32_e32 v131, v132, v131
	v_mul_f32_e32 v132, v99, v99
	v_mul_f32_e32 v133, v101, v101
	v_fmac_f32_e32 v132, v98, v98
	v_fmac_f32_e32 v133, v100, v100
	v_add_f32_e32 v132, v132, v133
	v_add_f32_e32 v131, v132, v131
	v_mov_b32_e32 v132, v131
	s_nop 1
	v_permlane16_swap_b32_e32 v131, v132
	v_add_f32_e32 v131, v131, v132
	v_mov_b32_e32 v132, v131
	s_nop 1
	v_permlane32_swap_b32_e32 v131, v132
	s_and_saveexec_b64 s[0:1], vcc
	v_add_f32_e32 v131, v131, v132
	ds_write_b32 v130, v131 offset:2304
	s_or_b64 exec, exec, s[0:1]
	v_mul_f32_e32 v131, v95, v95
	v_mul_f32_e32 v132, v97, v97
	v_fmac_f32_e32 v131, v94, v94
	v_fmac_f32_e32 v132, v96, v96
	v_add_f32_e32 v131, v131, v132
	v_mul_f32_e32 v132, v91, v91
	v_mul_f32_e32 v133, v93, v93
	v_fmac_f32_e32 v132, v90, v90
	v_fmac_f32_e32 v133, v92, v92
	v_add_f32_e32 v132, v132, v133
	v_add_f32_e32 v131, v131, v132
	v_mul_f32_e32 v132, v63, v63
	v_mul_f32_e32 v133, v65, v65
	v_fmac_f32_e32 v132, v62, v62
	v_fmac_f32_e32 v133, v64, v64
	v_add_f32_e32 v132, v132, v133
	v_add_f32_e32 v131, v132, v131
	v_mul_f32_e32 v132, v59, v59
	v_mul_f32_e32 v133, v61, v61
	v_fmac_f32_e32 v132, v58, v58
	v_fmac_f32_e32 v133, v60, v60
	v_add_f32_e32 v132, v132, v133
	v_add_f32_e32 v131, v132, v131
	v_mov_b32_e32 v132, v131
	s_nop 1
	v_permlane16_swap_b32_e32 v131, v132
	v_add_f32_e32 v131, v131, v132
	v_mov_b32_e32 v132, v131
	s_nop 1
	v_permlane32_swap_b32_e32 v131, v132
	s_and_saveexec_b64 s[0:1], vcc
	v_add_f32_e32 v131, v131, v132
	ds_write_b32 v130, v131 offset:2560
	s_or_b64 exec, exec, s[0:1]
	v_mul_f32_e32 v131, v39, v39
	v_mul_f32_e32 v132, v41, v41
	v_fmac_f32_e32 v131, v38, v38
	v_fmac_f32_e32 v132, v40, v40
	v_add_f32_e32 v131, v131, v132
	v_mul_f32_e32 v132, v35, v35
	v_mul_f32_e32 v133, v37, v37
	v_fmac_f32_e32 v132, v34, v34
	v_fmac_f32_e32 v133, v36, v36
	v_add_f32_e32 v132, v132, v133
	v_add_f32_e32 v131, v131, v132
	v_mul_f32_e32 v132, v7, v7
	v_mul_f32_e32 v133, v9, v9
	v_fmac_f32_e32 v132, v6, v6
	v_fmac_f32_e32 v133, v8, v8
	v_add_f32_e32 v132, v132, v133
	v_add_f32_e32 v131, v132, v131
	v_mul_f32_e32 v132, v3, v3
	v_mul_f32_e32 v133, v5, v5
	v_fmac_f32_e32 v132, v2, v2
	v_fmac_f32_e32 v133, v4, v4
	v_add_f32_e32 v132, v132, v133
	v_add_f32_e32 v131, v132, v131
	v_mov_b32_e32 v132, v131
	s_nop 1
	v_permlane16_swap_b32_e32 v131, v132
	v_add_f32_e32 v131, v131, v132
	v_mov_b32_e32 v132, v131
	s_nop 1
	v_permlane32_swap_b32_e32 v131, v132
	s_and_saveexec_b64 s[0:1], vcc
	v_add_f32_e32 v131, v131, v132
	ds_write_b32 v130, v131 offset:2816
	s_or_b64 exec, exec, s[0:1]
	s_waitcnt lgkmcnt(0)
	s_barrier
;     __device__ __forceinline__ void operator()(f32x4 (&acc)[2][2][4][2], const Unit& u, int wr, int wc, int fr_, int fq_) const {
;     ...
;         const int wid = wr * 4 + wc, lane = fq * 16 + fr, row = wid * 32 + (lane & 31);
;         if (lane < 32) { const float t = (P[row * 4 + 0] + P[row * 4 + 1]) + (P[row * 4 + 2] + P[row * 4 + 3]);
;             __hip_atomic_store(xbuf + ((size_t)u.pm * BM + row) * 8 + u.pn, t, __ATOMIC_RELAXED, __HIP_MEMORY_SCOPE_AGENT); }
	v_lshl_add_u32 v201, v169, 4, v168
	v_and_or_b32 v202, v201, 31, s56
	v_cmp_gt_i32_e64 s[8:9], 32, v201
	v_ashrrev_i32_e32 v203, 31, v202
	s_and_saveexec_b64 s[0:1], s[8:9]
	s_cbranch_execz .LBB0_1506
	v_lshl_add_u32 v130, v202, 4, 0
	v_add_u32_e32 v130, 0x20540, v130
	ds_read_b128 v[130:133], v130
	s_ashr_i32 s35, s34, 31
	s_lshl_b64 s[44:45], s[34:35], 13
	s_add_u32 s44, s96, s44
	s_addc_u32 s45, s97, s45
	s_waitcnt lgkmcnt(0)
	v_mov_b32_e32 v134, v131
	v_mov_b32_e32 v135, v132
	v_mov_b32_e32 v131, v133
	v_lshlrev_b64 v[132:133], 5, v[202:203]
	v_pk_add_f32 v[130:131], v[134:135], v[130:131]
	v_lshl_add_u64 v[132:133], s[44:45], 0, v[132:133]
	s_ashr_i32 s31, s30, 31
	v_pk_add_f32 v[130:131], v[130:131], v[130:131] op_sel:[0,1] op_sel_hi:[1,0]
	v_lshl_add_u64 v[132:133], s[30:31], 2, v[132:133]
	global_store_dword v[132:133], v130, off sc1
